# pool phase rewritten by hand: rolling 8-row prefetch pipeline with counted vmcnt instead of per-row vmcnt(0) round trips; bit-identical math
# speedup vs baseline: 1.0100x; 1.0100x over previous
.LBB0_382:
	s_or_b64 exec, exec, s[8:9]
	v_mov_b32_e32 v10, v1
	s_waitcnt lgkmcnt(0)
	s_barrier
	s_xor_b64 s[36:37], s[52:53], -1
	v_add_u32_e32 v3, s75, v1
	v_add_u32_e32 v3, s76, v3
	v_lshrrev_b32_e32 v3, 8, v3
	v_and_b32_e32 v2, 0xff, v1
	v_lshlrev_b32_e32 v2, 4, v2
	v_lshl_or_b32 v2, v3, 17, v2
	s_nop 0
	v_readfirstlane_b32 s100, v3
	v_readfirstlane_b32 s101, v1
	v_and_b32_e32 v3, 0xff, v1
	v_lshlrev_b32_e32 v3, 5, v3
	s_lshl_b32 s30, s64, 13
	s_add_u32 s98, s44, s30
	s_addc_u32 s99, s45, 0
	global_load_dwordx4 v[108:111], v3, s[98:99]
	global_load_dwordx4 v[112:115], v3, s[98:99] offset:16
	s_bfe_u32 s101, s101, 0x20006
	s_add_u32 s39, s101, 1
	s_lshl_b32 s38, s39, 23
	s_sub_u32 s38, 0x3f800000, s38
	s_lshl_b32 s101, 2, s101
	s_sub_u32 s101, s101, 1
	s_add_u32 s8, s84, 0xc000000
	s_addc_u32 s9, s85, 0
	s_mov_b64 s[10:11], s[50:51]
	s_add_u32 s12, s84, 0x14000000
	s_addc_u32 s13, s85, 0
	s_lshl_b32 s39, s101, 12
	s_sub_u32 s40, s8, s39
	s_subb_u32 s41, s9, 0
	s_and_b32 s100, s100, 0x7f
	s_cmp_eq_u32 s100, 0
	s_cselect_b32 s30, s101, 0
	s_mov_b32 s100, 0
	v_mov_b32_e32 v100, 0
	v_mov_b32_e32 v101, 0
	v_mov_b32_e32 v102, 0
	v_mov_b32_e32 v103, 0
	v_mov_b32_e32 v104, 0
	v_mov_b32_e32 v105, 0
	v_mov_b32_e32 v106, 0
	v_mov_b32_e32 v107, 0
	s_cmp_lg_u32 s30, 0
	s_cbranch_scc1 .Lpool_lb_done
	s_sub_u32 s98, s8, 0x1000
	s_subb_u32 s99, s9, 0
	global_load_dwordx4 v[36:39], v2, s[98:99]
	s_cmp_lt_u32 s101, 2
	s_cbranch_scc1 .Lpool_lb_issued
	s_sub_u32 s98, s8, 0x2000
	s_subb_u32 s99, s9, 0
	global_load_dwordx4 v[40:43], v2, s[98:99]
	s_sub_u32 s98, s8, 0x3000
	s_subb_u32 s99, s9, 0
	global_load_dwordx4 v[44:47], v2, s[98:99]
	s_cmp_lt_u32 s101, 4
	s_cbranch_scc1 .Lpool_lb_issued
	s_sub_u32 s98, s8, 0x4000
	s_subb_u32 s99, s9, 0
	global_load_dwordx4 v[48:51], v2, s[98:99]
	s_sub_u32 s98, s8, 0x5000
	s_subb_u32 s99, s9, 0
	global_load_dwordx4 v[52:55], v2, s[98:99]
	s_sub_u32 s98, s8, 0x6000
	s_subb_u32 s99, s9, 0
	global_load_dwordx4 v[56:59], v2, s[98:99]
	s_sub_u32 s98, s8, 0x7000
	s_subb_u32 s99, s9, 0
	global_load_dwordx4 v[60:63], v2, s[98:99]
	s_cmp_lt_u32 s101, 8
	s_cbranch_scc1 .Lpool_lb_issued
	s_sub_u32 s98, s8, 0x8000
	s_subb_u32 s99, s9, 0
	global_load_dwordx4 v[64:67], v2, s[98:99]
	s_sub_u32 s98, s8, 0x9000
	s_subb_u32 s99, s9, 0
	global_load_dwordx4 v[68:71], v2, s[98:99]
	s_sub_u32 s98, s8, 0xa000
	s_subb_u32 s99, s9, 0
	global_load_dwordx4 v[72:75], v2, s[98:99]
	s_sub_u32 s98, s8, 0xb000
	s_subb_u32 s99, s9, 0
	global_load_dwordx4 v[76:79], v2, s[98:99]
	s_sub_u32 s98, s8, 0xc000
	s_subb_u32 s99, s9, 0
	global_load_dwordx4 v[80:83], v2, s[98:99]
	s_sub_u32 s98, s8, 0xd000
	s_subb_u32 s99, s9, 0
	global_load_dwordx4 v[84:87], v2, s[98:99]
	s_sub_u32 s98, s8, 0xe000
	s_subb_u32 s99, s9, 0
	global_load_dwordx4 v[88:91], v2, s[98:99]
	s_sub_u32 s98, s8, 0xf000
	s_subb_u32 s99, s9, 0
	global_load_dwordx4 v[92:95], v2, s[98:99]
.Lpool_lb_issued:
	s_waitcnt vmcnt(0)
	v_lshlrev_b32_e32 v116, 16, v36
	v_and_b32_e32 v117, 0xffff0000, v36
	v_lshlrev_b32_e32 v118, 16, v37
	v_and_b32_e32 v119, 0xffff0000, v37
	v_lshlrev_b32_e32 v120, 16, v38
	v_and_b32_e32 v121, 0xffff0000, v38
	v_lshlrev_b32_e32 v122, 16, v39
	v_and_b32_e32 v123, 0xffff0000, v39
	v_pk_add_f32 v[100:101], v[100:101], v[116:117]
	v_pk_add_f32 v[102:103], v[102:103], v[118:119]
	v_pk_add_f32 v[104:105], v[104:105], v[120:121]
	v_pk_add_f32 v[106:107], v[106:107], v[122:123]
	s_cmp_lt_u32 s101, 2
	s_cbranch_scc1 .Lpool_lb_done
	v_lshlrev_b32_e32 v116, 16, v40
	v_and_b32_e32 v117, 0xffff0000, v40
	v_lshlrev_b32_e32 v118, 16, v41
	v_and_b32_e32 v119, 0xffff0000, v41
	v_lshlrev_b32_e32 v120, 16, v42
	v_and_b32_e32 v121, 0xffff0000, v42
	v_lshlrev_b32_e32 v122, 16, v43
	v_and_b32_e32 v123, 0xffff0000, v43
	v_pk_add_f32 v[100:101], v[100:101], v[116:117]
	v_pk_add_f32 v[102:103], v[102:103], v[118:119]
	v_pk_add_f32 v[104:105], v[104:105], v[120:121]
	v_pk_add_f32 v[106:107], v[106:107], v[122:123]
	v_lshlrev_b32_e32 v116, 16, v44
	v_and_b32_e32 v117, 0xffff0000, v44
	v_lshlrev_b32_e32 v118, 16, v45
	v_and_b32_e32 v119, 0xffff0000, v45
	v_lshlrev_b32_e32 v120, 16, v46
	v_and_b32_e32 v121, 0xffff0000, v46
	v_lshlrev_b32_e32 v122, 16, v47
	v_and_b32_e32 v123, 0xffff0000, v47
	v_pk_add_f32 v[100:101], v[100:101], v[116:117]
	v_pk_add_f32 v[102:103], v[102:103], v[118:119]
	v_pk_add_f32 v[104:105], v[104:105], v[120:121]
	v_pk_add_f32 v[106:107], v[106:107], v[122:123]
	s_cmp_lt_u32 s101, 4
	s_cbranch_scc1 .Lpool_lb_done
	v_lshlrev_b32_e32 v116, 16, v48
	v_and_b32_e32 v117, 0xffff0000, v48
	v_lshlrev_b32_e32 v118, 16, v49
	v_and_b32_e32 v119, 0xffff0000, v49
	v_lshlrev_b32_e32 v120, 16, v50
	v_and_b32_e32 v121, 0xffff0000, v50
	v_lshlrev_b32_e32 v122, 16, v51
	v_and_b32_e32 v123, 0xffff0000, v51
	v_pk_add_f32 v[100:101], v[100:101], v[116:117]
	v_pk_add_f32 v[102:103], v[102:103], v[118:119]
	v_pk_add_f32 v[104:105], v[104:105], v[120:121]
	v_pk_add_f32 v[106:107], v[106:107], v[122:123]
	v_lshlrev_b32_e32 v116, 16, v52
	v_and_b32_e32 v117, 0xffff0000, v52
	v_lshlrev_b32_e32 v118, 16, v53
	v_and_b32_e32 v119, 0xffff0000, v53
	v_lshlrev_b32_e32 v120, 16, v54
	v_and_b32_e32 v121, 0xffff0000, v54
	v_lshlrev_b32_e32 v122, 16, v55
	v_and_b32_e32 v123, 0xffff0000, v55
	v_pk_add_f32 v[100:101], v[100:101], v[116:117]
	v_pk_add_f32 v[102:103], v[102:103], v[118:119]
	v_pk_add_f32 v[104:105], v[104:105], v[120:121]
	v_pk_add_f32 v[106:107], v[106:107], v[122:123]
	v_lshlrev_b32_e32 v116, 16, v56
	v_and_b32_e32 v117, 0xffff0000, v56
	v_lshlrev_b32_e32 v118, 16, v57
	v_and_b32_e32 v119, 0xffff0000, v57
	v_lshlrev_b32_e32 v120, 16, v58
	v_and_b32_e32 v121, 0xffff0000, v58
	v_lshlrev_b32_e32 v122, 16, v59
	v_and_b32_e32 v123, 0xffff0000, v59
	v_pk_add_f32 v[100:101], v[100:101], v[116:117]
	v_pk_add_f32 v[102:103], v[102:103], v[118:119]
	v_pk_add_f32 v[104:105], v[104:105], v[120:121]
	v_pk_add_f32 v[106:107], v[106:107], v[122:123]
	v_lshlrev_b32_e32 v116, 16, v60
	v_and_b32_e32 v117, 0xffff0000, v60
	v_lshlrev_b32_e32 v118, 16, v61
	v_and_b32_e32 v119, 0xffff0000, v61
	v_lshlrev_b32_e32 v120, 16, v62
	v_and_b32_e32 v121, 0xffff0000, v62
	v_lshlrev_b32_e32 v122, 16, v63
	v_and_b32_e32 v123, 0xffff0000, v63
	v_pk_add_f32 v[100:101], v[100:101], v[116:117]
	v_pk_add_f32 v[102:103], v[102:103], v[118:119]
	v_pk_add_f32 v[104:105], v[104:105], v[120:121]
	v_pk_add_f32 v[106:107], v[106:107], v[122:123]
	s_cmp_lt_u32 s101, 8
	s_cbranch_scc1 .Lpool_lb_done
	v_lshlrev_b32_e32 v116, 16, v64
	v_and_b32_e32 v117, 0xffff0000, v64
	v_lshlrev_b32_e32 v118, 16, v65
	v_and_b32_e32 v119, 0xffff0000, v65
	v_lshlrev_b32_e32 v120, 16, v66
	v_and_b32_e32 v121, 0xffff0000, v66
	v_lshlrev_b32_e32 v122, 16, v67
	v_and_b32_e32 v123, 0xffff0000, v67
	v_pk_add_f32 v[100:101], v[100:101], v[116:117]
	v_pk_add_f32 v[102:103], v[102:103], v[118:119]
	v_pk_add_f32 v[104:105], v[104:105], v[120:121]
	v_pk_add_f32 v[106:107], v[106:107], v[122:123]
	v_lshlrev_b32_e32 v116, 16, v68
	v_and_b32_e32 v117, 0xffff0000, v68
	v_lshlrev_b32_e32 v118, 16, v69
	v_and_b32_e32 v119, 0xffff0000, v69
	v_lshlrev_b32_e32 v120, 16, v70
	v_and_b32_e32 v121, 0xffff0000, v70
	v_lshlrev_b32_e32 v122, 16, v71
	v_and_b32_e32 v123, 0xffff0000, v71
	v_pk_add_f32 v[100:101], v[100:101], v[116:117]
	v_pk_add_f32 v[102:103], v[102:103], v[118:119]
	v_pk_add_f32 v[104:105], v[104:105], v[120:121]
	v_pk_add_f32 v[106:107], v[106:107], v[122:123]
	v_lshlrev_b32_e32 v116, 16, v72
	v_and_b32_e32 v117, 0xffff0000, v72
	v_lshlrev_b32_e32 v118, 16, v73
	v_and_b32_e32 v119, 0xffff0000, v73
	v_lshlrev_b32_e32 v120, 16, v74
	v_and_b32_e32 v121, 0xffff0000, v74
	v_lshlrev_b32_e32 v122, 16, v75
	v_and_b32_e32 v123, 0xffff0000, v75
	v_pk_add_f32 v[100:101], v[100:101], v[116:117]
	v_pk_add_f32 v[102:103], v[102:103], v[118:119]
	v_pk_add_f32 v[104:105], v[104:105], v[120:121]
	v_pk_add_f32 v[106:107], v[106:107], v[122:123]
	v_lshlrev_b32_e32 v116, 16, v76
	v_and_b32_e32 v117, 0xffff0000, v76
	v_lshlrev_b32_e32 v118, 16, v77
	v_and_b32_e32 v119, 0xffff0000, v77
	v_lshlrev_b32_e32 v120, 16, v78
	v_and_b32_e32 v121, 0xffff0000, v78
	v_lshlrev_b32_e32 v122, 16, v79
	v_and_b32_e32 v123, 0xffff0000, v79
	v_pk_add_f32 v[100:101], v[100:101], v[116:117]
	v_pk_add_f32 v[102:103], v[102:103], v[118:119]
	v_pk_add_f32 v[104:105], v[104:105], v[120:121]
	v_pk_add_f32 v[106:107], v[106:107], v[122:123]
	v_lshlrev_b32_e32 v116, 16, v80
	v_and_b32_e32 v117, 0xffff0000, v80
	v_lshlrev_b32_e32 v118, 16, v81
	v_and_b32_e32 v119, 0xffff0000, v81
	v_lshlrev_b32_e32 v120, 16, v82
	v_and_b32_e32 v121, 0xffff0000, v82
	v_lshlrev_b32_e32 v122, 16, v83
	v_and_b32_e32 v123, 0xffff0000, v83
	v_pk_add_f32 v[100:101], v[100:101], v[116:117]
	v_pk_add_f32 v[102:103], v[102:103], v[118:119]
	v_pk_add_f32 v[104:105], v[104:105], v[120:121]
	v_pk_add_f32 v[106:107], v[106:107], v[122:123]
	v_lshlrev_b32_e32 v116, 16, v84
	v_and_b32_e32 v117, 0xffff0000, v84
	v_lshlrev_b32_e32 v118, 16, v85
	v_and_b32_e32 v119, 0xffff0000, v85
	v_lshlrev_b32_e32 v120, 16, v86
	v_and_b32_e32 v121, 0xffff0000, v86
	v_lshlrev_b32_e32 v122, 16, v87
	v_and_b32_e32 v123, 0xffff0000, v87
	v_pk_add_f32 v[100:101], v[100:101], v[116:117]
	v_pk_add_f32 v[102:103], v[102:103], v[118:119]
	v_pk_add_f32 v[104:105], v[104:105], v[120:121]
	v_pk_add_f32 v[106:107], v[106:107], v[122:123]
	v_lshlrev_b32_e32 v116, 16, v88
	v_and_b32_e32 v117, 0xffff0000, v88
	v_lshlrev_b32_e32 v118, 16, v89
	v_and_b32_e32 v119, 0xffff0000, v89
	v_lshlrev_b32_e32 v120, 16, v90
	v_and_b32_e32 v121, 0xffff0000, v90
	v_lshlrev_b32_e32 v122, 16, v91
	v_and_b32_e32 v123, 0xffff0000, v91
	v_pk_add_f32 v[100:101], v[100:101], v[116:117]
	v_pk_add_f32 v[102:103], v[102:103], v[118:119]
	v_pk_add_f32 v[104:105], v[104:105], v[120:121]
	v_pk_add_f32 v[106:107], v[106:107], v[122:123]
	v_lshlrev_b32_e32 v116, 16, v92
	v_and_b32_e32 v117, 0xffff0000, v92
	v_lshlrev_b32_e32 v118, 16, v93
	v_and_b32_e32 v119, 0xffff0000, v93
	v_lshlrev_b32_e32 v120, 16, v94
	v_and_b32_e32 v121, 0xffff0000, v94
	v_lshlrev_b32_e32 v122, 16, v95
	v_and_b32_e32 v123, 0xffff0000, v95
	v_pk_add_f32 v[100:101], v[100:101], v[116:117]
	v_pk_add_f32 v[102:103], v[102:103], v[118:119]
	v_pk_add_f32 v[104:105], v[104:105], v[120:121]
	v_pk_add_f32 v[106:107], v[106:107], v[122:123]
.Lpool_lb_done:
	s_add_u32 s98, s8, 0x0
	s_addc_u32 s99, s9, 0
	global_load_dwordx4 v[4:7], v2, s[98:99]
	s_add_u32 s98, s10, 0x0
	s_addc_u32 s99, s11, 0
	global_load_dwordx4 v[36:39], v2, s[98:99]
	s_add_u32 s98, s40, 0x0
	s_addc_u32 s99, s41, 0
	global_load_dwordx4 v[68:71], v2, s[98:99]
	s_add_u32 s98, s8, 0x1000
	s_addc_u32 s99, s9, 0
	global_load_dwordx4 v[8:11], v2, s[98:99]
	s_add_u32 s98, s10, 0x1000
	s_addc_u32 s99, s11, 0
	global_load_dwordx4 v[40:43], v2, s[98:99]
	s_add_u32 s98, s40, 0x1000
	s_addc_u32 s99, s41, 0
	global_load_dwordx4 v[72:75], v2, s[98:99]
	s_add_u32 s98, s8, 0x2000
	s_addc_u32 s99, s9, 0
	global_load_dwordx4 v[12:15], v2, s[98:99]
	s_add_u32 s98, s10, 0x2000
	s_addc_u32 s99, s11, 0
	global_load_dwordx4 v[44:47], v2, s[98:99]
	s_add_u32 s98, s40, 0x2000
	s_addc_u32 s99, s41, 0
	global_load_dwordx4 v[76:79], v2, s[98:99]
	s_add_u32 s98, s8, 0x3000
	s_addc_u32 s99, s9, 0
	global_load_dwordx4 v[16:19], v2, s[98:99]
	s_add_u32 s98, s10, 0x3000
	s_addc_u32 s99, s11, 0
	global_load_dwordx4 v[48:51], v2, s[98:99]
	s_add_u32 s98, s40, 0x3000
	s_addc_u32 s99, s41, 0
	global_load_dwordx4 v[80:83], v2, s[98:99]
	s_add_u32 s98, s8, 0x4000
	s_addc_u32 s99, s9, 0
	global_load_dwordx4 v[20:23], v2, s[98:99]
	s_add_u32 s98, s10, 0x4000
	s_addc_u32 s99, s11, 0
	global_load_dwordx4 v[52:55], v2, s[98:99]
	s_add_u32 s98, s40, 0x4000
	s_addc_u32 s99, s41, 0
	global_load_dwordx4 v[84:87], v2, s[98:99]
	s_add_u32 s98, s8, 0x5000
	s_addc_u32 s99, s9, 0
	global_load_dwordx4 v[24:27], v2, s[98:99]
	s_add_u32 s98, s10, 0x5000
	s_addc_u32 s99, s11, 0
	global_load_dwordx4 v[56:59], v2, s[98:99]
	s_add_u32 s98, s40, 0x5000
	s_addc_u32 s99, s41, 0
	global_load_dwordx4 v[88:91], v2, s[98:99]
	s_add_u32 s98, s8, 0x6000
	s_addc_u32 s99, s9, 0
	global_load_dwordx4 v[28:31], v2, s[98:99]
	s_add_u32 s98, s10, 0x6000
	s_addc_u32 s99, s11, 0
	global_load_dwordx4 v[60:63], v2, s[98:99]
	s_add_u32 s98, s40, 0x6000
	s_addc_u32 s99, s41, 0
	global_load_dwordx4 v[92:95], v2, s[98:99]
	s_add_u32 s98, s8, 0x7000
	s_addc_u32 s99, s9, 0
	global_load_dwordx4 v[32:35], v2, s[98:99]
	s_add_u32 s98, s10, 0x7000
	s_addc_u32 s99, s11, 0
	global_load_dwordx4 v[64:67], v2, s[98:99]
	s_add_u32 s98, s40, 0x7000
	s_addc_u32 s99, s41, 0
	global_load_dwordx4 v[96:99], v2, s[98:99]
	s_waitcnt vmcnt(0)
	s_mov_b32 s39, 3
.Lpool_batch:
	s_waitcnt vmcnt(28)
	v_mov_b32_e32 v154, s38
	s_cmp_lt_u32 s100, s30
	s_cbranch_scc0 .Lpool_fa_0
	v_mov_b32_e32 v68, 0
	v_mov_b32_e32 v69, 0
	v_mov_b32_e32 v70, 0
	v_mov_b32_e32 v71, 0
	s_add_u32 s98, s100, 1
	v_cvt_f32_u32_e32 v116, s98
	v_div_scale_f32 v117, s[98:99], v116, v116, 1.0
	v_rcp_f32_e32 v118, v117
	s_nop 1
	v_fma_f32 v119, -v117, v118, 1.0
	v_fmac_f32_e32 v118, v119, v118
	v_div_scale_f32 v119, vcc, 1.0, v116, 1.0
	v_mul_f32_e32 v120, v119, v118
	v_fma_f32 v121, -v117, v120, v119
	v_fmac_f32_e32 v120, v121, v118
	v_fma_f32 v117, -v117, v120, v119
	s_nop 1
	v_div_fmas_f32 v117, v117, v118, v120
	v_div_fixup_f32 v154, v117, v116, 1.0
.Lpool_fa_0:
	v_lshlrev_b32_e32 v116, 16, v4
	v_and_b32_e32 v117, 0xffff0000, v4
	v_lshlrev_b32_e32 v118, 16, v5
	v_and_b32_e32 v119, 0xffff0000, v5
	v_lshlrev_b32_e32 v120, 16, v6
	v_and_b32_e32 v121, 0xffff0000, v6
	v_lshlrev_b32_e32 v122, 16, v7
	v_and_b32_e32 v123, 0xffff0000, v7
	v_pk_add_f32 v[100:101], v[100:101], v[116:117]
	v_pk_add_f32 v[102:103], v[102:103], v[118:119]
	v_pk_add_f32 v[104:105], v[104:105], v[120:121]
	v_pk_add_f32 v[106:107], v[106:107], v[122:123]
	v_fma_f32 v116, v154, v100, -v116
	v_fma_f32 v117, v154, v101, -v117
	v_fma_f32 v118, v154, v102, -v118
	v_fma_f32 v119, v154, v103, -v119
	v_fma_f32 v120, v154, v104, -v120
	v_fma_f32 v121, v154, v105, -v121
	v_fma_f32 v122, v154, v106, -v122
	v_fma_f32 v123, v154, v107, -v123
	v_mul_f32_e32 v116, v108, v116
	v_mul_f32_e32 v117, v109, v117
	v_mul_f32_e32 v118, v110, v118
	v_mul_f32_e32 v119, v111, v119
	v_mul_f32_e32 v120, v112, v120
	v_mul_f32_e32 v121, v113, v121
	v_mul_f32_e32 v122, v114, v122
	v_mul_f32_e32 v123, v115, v123
	v_lshlrev_b32_e32 v128, 16, v36
	v_and_b32_e32 v129, 0xffff0000, v36
	v_mul_f32_e32 v116, v116, v128
	v_mul_f32_e32 v117, v117, v129
	v_cvt_pk_bf16_f32 v124, v116, v117
	v_lshlrev_b32_e32 v128, 16, v37
	v_and_b32_e32 v129, 0xffff0000, v37
	v_mul_f32_e32 v118, v118, v128
	v_mul_f32_e32 v119, v119, v129
	v_cvt_pk_bf16_f32 v125, v118, v119
	v_lshlrev_b32_e32 v128, 16, v38
	v_and_b32_e32 v129, 0xffff0000, v38
	v_mul_f32_e32 v120, v120, v128
	v_mul_f32_e32 v121, v121, v129
	v_cvt_pk_bf16_f32 v126, v120, v121
	v_lshlrev_b32_e32 v128, 16, v39
	v_and_b32_e32 v129, 0xffff0000, v39
	v_mul_f32_e32 v122, v122, v128
	v_mul_f32_e32 v123, v123, v129
	v_cvt_pk_bf16_f32 v127, v122, v123
	s_add_u32 s98, s12, 0
	s_addc_u32 s99, s13, 0
	global_store_dwordx4 v2, v[124:127], s[98:99]
	v_lshlrev_b32_e32 v116, 16, v68
	v_and_b32_e32 v117, 0xffff0000, v68
	v_lshlrev_b32_e32 v118, 16, v69
	v_and_b32_e32 v119, 0xffff0000, v69
	v_lshlrev_b32_e32 v120, 16, v70
	v_and_b32_e32 v121, 0xffff0000, v70
	v_lshlrev_b32_e32 v122, 16, v71
	v_and_b32_e32 v123, 0xffff0000, v71
	v_pk_add_f32 v[100:101], v[100:101], v[116:117] neg_lo:[0,1] neg_hi:[0,1]
	v_pk_add_f32 v[102:103], v[102:103], v[118:119] neg_lo:[0,1] neg_hi:[0,1]
	v_pk_add_f32 v[104:105], v[104:105], v[120:121] neg_lo:[0,1] neg_hi:[0,1]
	v_pk_add_f32 v[106:107], v[106:107], v[122:123] neg_lo:[0,1] neg_hi:[0,1]
	s_add_u32 s98, s8, 0x8000
	s_addc_u32 s99, s9, 0
	global_load_dwordx4 v[4:7], v2, s[98:99]
	s_add_u32 s98, s10, 0x8000
	s_addc_u32 s99, s11, 0
	global_load_dwordx4 v[36:39], v2, s[98:99]
	s_add_u32 s98, s40, 0x8000
	s_addc_u32 s99, s41, 0
	global_load_dwordx4 v[68:71], v2, s[98:99]
	s_add_u32 s100, s100, 1
	s_waitcnt vmcnt(28)
	v_mov_b32_e32 v154, s38
	s_cmp_lt_u32 s100, s30
	s_cbranch_scc0 .Lpool_fa_1
	v_mov_b32_e32 v72, 0
	v_mov_b32_e32 v73, 0
	v_mov_b32_e32 v74, 0
	v_mov_b32_e32 v75, 0
	s_add_u32 s98, s100, 1
	v_cvt_f32_u32_e32 v116, s98
	v_div_scale_f32 v117, s[98:99], v116, v116, 1.0
	v_rcp_f32_e32 v118, v117
	s_nop 1
	v_fma_f32 v119, -v117, v118, 1.0
	v_fmac_f32_e32 v118, v119, v118
	v_div_scale_f32 v119, vcc, 1.0, v116, 1.0
	v_mul_f32_e32 v120, v119, v118
	v_fma_f32 v121, -v117, v120, v119
	v_fmac_f32_e32 v120, v121, v118
	v_fma_f32 v117, -v117, v120, v119
	s_nop 1
	v_div_fmas_f32 v117, v117, v118, v120
	v_div_fixup_f32 v154, v117, v116, 1.0
.Lpool_fa_1:
	v_lshlrev_b32_e32 v116, 16, v8
	v_and_b32_e32 v117, 0xffff0000, v8
	v_lshlrev_b32_e32 v118, 16, v9
	v_and_b32_e32 v119, 0xffff0000, v9
	v_lshlrev_b32_e32 v120, 16, v10
	v_and_b32_e32 v121, 0xffff0000, v10
	v_lshlrev_b32_e32 v122, 16, v11
	v_and_b32_e32 v123, 0xffff0000, v11
	v_pk_add_f32 v[100:101], v[100:101], v[116:117]
	v_pk_add_f32 v[102:103], v[102:103], v[118:119]
	v_pk_add_f32 v[104:105], v[104:105], v[120:121]
	v_pk_add_f32 v[106:107], v[106:107], v[122:123]
	v_fma_f32 v116, v154, v100, -v116
	v_fma_f32 v117, v154, v101, -v117
	v_fma_f32 v118, v154, v102, -v118
	v_fma_f32 v119, v154, v103, -v119
	v_fma_f32 v120, v154, v104, -v120
	v_fma_f32 v121, v154, v105, -v121
	v_fma_f32 v122, v154, v106, -v122
	v_fma_f32 v123, v154, v107, -v123
	v_mul_f32_e32 v116, v108, v116
	v_mul_f32_e32 v117, v109, v117
	v_mul_f32_e32 v118, v110, v118
	v_mul_f32_e32 v119, v111, v119
	v_mul_f32_e32 v120, v112, v120
	v_mul_f32_e32 v121, v113, v121
	v_mul_f32_e32 v122, v114, v122
	v_mul_f32_e32 v123, v115, v123
	v_lshlrev_b32_e32 v128, 16, v40
	v_and_b32_e32 v129, 0xffff0000, v40
	v_mul_f32_e32 v116, v116, v128
	v_mul_f32_e32 v117, v117, v129
	v_cvt_pk_bf16_f32 v124, v116, v117
	v_lshlrev_b32_e32 v128, 16, v41
	v_and_b32_e32 v129, 0xffff0000, v41
	v_mul_f32_e32 v118, v118, v128
	v_mul_f32_e32 v119, v119, v129
	v_cvt_pk_bf16_f32 v125, v118, v119
	v_lshlrev_b32_e32 v128, 16, v42
	v_and_b32_e32 v129, 0xffff0000, v42
	v_mul_f32_e32 v120, v120, v128
	v_mul_f32_e32 v121, v121, v129
	v_cvt_pk_bf16_f32 v126, v120, v121
	v_lshlrev_b32_e32 v128, 16, v43
	v_and_b32_e32 v129, 0xffff0000, v43
	v_mul_f32_e32 v122, v122, v128
	v_mul_f32_e32 v123, v123, v129
	v_cvt_pk_bf16_f32 v127, v122, v123
	s_add_u32 s98, s12, 0x1000
	s_addc_u32 s99, s13, 0
	global_store_dwordx4 v2, v[124:127], s[98:99]
	v_lshlrev_b32_e32 v116, 16, v72
	v_and_b32_e32 v117, 0xffff0000, v72
	v_lshlrev_b32_e32 v118, 16, v73
	v_and_b32_e32 v119, 0xffff0000, v73
	v_lshlrev_b32_e32 v120, 16, v74
	v_and_b32_e32 v121, 0xffff0000, v74
	v_lshlrev_b32_e32 v122, 16, v75
	v_and_b32_e32 v123, 0xffff0000, v75
	v_pk_add_f32 v[100:101], v[100:101], v[116:117] neg_lo:[0,1] neg_hi:[0,1]
	v_pk_add_f32 v[102:103], v[102:103], v[118:119] neg_lo:[0,1] neg_hi:[0,1]
	v_pk_add_f32 v[104:105], v[104:105], v[120:121] neg_lo:[0,1] neg_hi:[0,1]
	v_pk_add_f32 v[106:107], v[106:107], v[122:123] neg_lo:[0,1] neg_hi:[0,1]
	s_add_u32 s98, s8, 0x9000
	s_addc_u32 s99, s9, 0
	global_load_dwordx4 v[8:11], v2, s[98:99]
	s_add_u32 s98, s10, 0x9000
	s_addc_u32 s99, s11, 0
	global_load_dwordx4 v[40:43], v2, s[98:99]
	s_add_u32 s98, s40, 0x9000
	s_addc_u32 s99, s41, 0
	global_load_dwordx4 v[72:75], v2, s[98:99]
	s_add_u32 s100, s100, 1
	s_waitcnt vmcnt(28)
	v_mov_b32_e32 v154, s38
	s_cmp_lt_u32 s100, s30
	s_cbranch_scc0 .Lpool_fa_2
	v_mov_b32_e32 v76, 0
	v_mov_b32_e32 v77, 0
	v_mov_b32_e32 v78, 0
	v_mov_b32_e32 v79, 0
	s_add_u32 s98, s100, 1
	v_cvt_f32_u32_e32 v116, s98
	v_div_scale_f32 v117, s[98:99], v116, v116, 1.0
	v_rcp_f32_e32 v118, v117
	s_nop 1
	v_fma_f32 v119, -v117, v118, 1.0
	v_fmac_f32_e32 v118, v119, v118
	v_div_scale_f32 v119, vcc, 1.0, v116, 1.0
	v_mul_f32_e32 v120, v119, v118
	v_fma_f32 v121, -v117, v120, v119
	v_fmac_f32_e32 v120, v121, v118
	v_fma_f32 v117, -v117, v120, v119
	s_nop 1
	v_div_fmas_f32 v117, v117, v118, v120
	v_div_fixup_f32 v154, v117, v116, 1.0
.Lpool_fa_2:
	v_lshlrev_b32_e32 v116, 16, v12
	v_and_b32_e32 v117, 0xffff0000, v12
	v_lshlrev_b32_e32 v118, 16, v13
	v_and_b32_e32 v119, 0xffff0000, v13
	v_lshlrev_b32_e32 v120, 16, v14
	v_and_b32_e32 v121, 0xffff0000, v14
	v_lshlrev_b32_e32 v122, 16, v15
	v_and_b32_e32 v123, 0xffff0000, v15
	v_pk_add_f32 v[100:101], v[100:101], v[116:117]
	v_pk_add_f32 v[102:103], v[102:103], v[118:119]
	v_pk_add_f32 v[104:105], v[104:105], v[120:121]
	v_pk_add_f32 v[106:107], v[106:107], v[122:123]
	v_fma_f32 v116, v154, v100, -v116
	v_fma_f32 v117, v154, v101, -v117
	v_fma_f32 v118, v154, v102, -v118
	v_fma_f32 v119, v154, v103, -v119
	v_fma_f32 v120, v154, v104, -v120
	v_fma_f32 v121, v154, v105, -v121
	v_fma_f32 v122, v154, v106, -v122
	v_fma_f32 v123, v154, v107, -v123
	v_mul_f32_e32 v116, v108, v116
	v_mul_f32_e32 v117, v109, v117
	v_mul_f32_e32 v118, v110, v118
	v_mul_f32_e32 v119, v111, v119
	v_mul_f32_e32 v120, v112, v120
	v_mul_f32_e32 v121, v113, v121
	v_mul_f32_e32 v122, v114, v122
	v_mul_f32_e32 v123, v115, v123
	v_lshlrev_b32_e32 v128, 16, v44
	v_and_b32_e32 v129, 0xffff0000, v44
	v_mul_f32_e32 v116, v116, v128
	v_mul_f32_e32 v117, v117, v129
	v_cvt_pk_bf16_f32 v124, v116, v117
	v_lshlrev_b32_e32 v128, 16, v45
	v_and_b32_e32 v129, 0xffff0000, v45
	v_mul_f32_e32 v118, v118, v128
	v_mul_f32_e32 v119, v119, v129
	v_cvt_pk_bf16_f32 v125, v118, v119
	v_lshlrev_b32_e32 v128, 16, v46
	v_and_b32_e32 v129, 0xffff0000, v46
	v_mul_f32_e32 v120, v120, v128
	v_mul_f32_e32 v121, v121, v129
	v_cvt_pk_bf16_f32 v126, v120, v121
	v_lshlrev_b32_e32 v128, 16, v47
	v_and_b32_e32 v129, 0xffff0000, v47
	v_mul_f32_e32 v122, v122, v128
	v_mul_f32_e32 v123, v123, v129
	v_cvt_pk_bf16_f32 v127, v122, v123
	s_add_u32 s98, s12, 0x2000
	s_addc_u32 s99, s13, 0
	global_store_dwordx4 v2, v[124:127], s[98:99]
	v_lshlrev_b32_e32 v116, 16, v76
	v_and_b32_e32 v117, 0xffff0000, v76
	v_lshlrev_b32_e32 v118, 16, v77
	v_and_b32_e32 v119, 0xffff0000, v77
	v_lshlrev_b32_e32 v120, 16, v78
	v_and_b32_e32 v121, 0xffff0000, v78
	v_lshlrev_b32_e32 v122, 16, v79
	v_and_b32_e32 v123, 0xffff0000, v79
	v_pk_add_f32 v[100:101], v[100:101], v[116:117] neg_lo:[0,1] neg_hi:[0,1]
	v_pk_add_f32 v[102:103], v[102:103], v[118:119] neg_lo:[0,1] neg_hi:[0,1]
	v_pk_add_f32 v[104:105], v[104:105], v[120:121] neg_lo:[0,1] neg_hi:[0,1]
	v_pk_add_f32 v[106:107], v[106:107], v[122:123] neg_lo:[0,1] neg_hi:[0,1]
	s_add_u32 s98, s8, 0xa000
	s_addc_u32 s99, s9, 0
	global_load_dwordx4 v[12:15], v2, s[98:99]
	s_add_u32 s98, s10, 0xa000
	s_addc_u32 s99, s11, 0
	global_load_dwordx4 v[44:47], v2, s[98:99]
	s_add_u32 s98, s40, 0xa000
	s_addc_u32 s99, s41, 0
	global_load_dwordx4 v[76:79], v2, s[98:99]
	s_add_u32 s100, s100, 1
	s_waitcnt vmcnt(28)
	v_mov_b32_e32 v154, s38
	s_cmp_lt_u32 s100, s30
	s_cbranch_scc0 .Lpool_fa_3
	v_mov_b32_e32 v80, 0
	v_mov_b32_e32 v81, 0
	v_mov_b32_e32 v82, 0
	v_mov_b32_e32 v83, 0
	s_add_u32 s98, s100, 1
	v_cvt_f32_u32_e32 v116, s98
	v_div_scale_f32 v117, s[98:99], v116, v116, 1.0
	v_rcp_f32_e32 v118, v117
	s_nop 1
	v_fma_f32 v119, -v117, v118, 1.0
	v_fmac_f32_e32 v118, v119, v118
	v_div_scale_f32 v119, vcc, 1.0, v116, 1.0
	v_mul_f32_e32 v120, v119, v118
	v_fma_f32 v121, -v117, v120, v119
	v_fmac_f32_e32 v120, v121, v118
	v_fma_f32 v117, -v117, v120, v119
	s_nop 1
	v_div_fmas_f32 v117, v117, v118, v120
	v_div_fixup_f32 v154, v117, v116, 1.0
.Lpool_fa_3:
	v_lshlrev_b32_e32 v116, 16, v16
	v_and_b32_e32 v117, 0xffff0000, v16
	v_lshlrev_b32_e32 v118, 16, v17
	v_and_b32_e32 v119, 0xffff0000, v17
	v_lshlrev_b32_e32 v120, 16, v18
	v_and_b32_e32 v121, 0xffff0000, v18
	v_lshlrev_b32_e32 v122, 16, v19
	v_and_b32_e32 v123, 0xffff0000, v19
	v_pk_add_f32 v[100:101], v[100:101], v[116:117]
	v_pk_add_f32 v[102:103], v[102:103], v[118:119]
	v_pk_add_f32 v[104:105], v[104:105], v[120:121]
	v_pk_add_f32 v[106:107], v[106:107], v[122:123]
	v_fma_f32 v116, v154, v100, -v116
	v_fma_f32 v117, v154, v101, -v117
	v_fma_f32 v118, v154, v102, -v118
	v_fma_f32 v119, v154, v103, -v119
	v_fma_f32 v120, v154, v104, -v120
	v_fma_f32 v121, v154, v105, -v121
	v_fma_f32 v122, v154, v106, -v122
	v_fma_f32 v123, v154, v107, -v123
	v_mul_f32_e32 v116, v108, v116
	v_mul_f32_e32 v117, v109, v117
	v_mul_f32_e32 v118, v110, v118
	v_mul_f32_e32 v119, v111, v119
	v_mul_f32_e32 v120, v112, v120
	v_mul_f32_e32 v121, v113, v121
	v_mul_f32_e32 v122, v114, v122
	v_mul_f32_e32 v123, v115, v123
	v_lshlrev_b32_e32 v128, 16, v48
	v_and_b32_e32 v129, 0xffff0000, v48
	v_mul_f32_e32 v116, v116, v128
	v_mul_f32_e32 v117, v117, v129
	v_cvt_pk_bf16_f32 v124, v116, v117
	v_lshlrev_b32_e32 v128, 16, v49
	v_and_b32_e32 v129, 0xffff0000, v49
	v_mul_f32_e32 v118, v118, v128
	v_mul_f32_e32 v119, v119, v129
	v_cvt_pk_bf16_f32 v125, v118, v119
	v_lshlrev_b32_e32 v128, 16, v50
	v_and_b32_e32 v129, 0xffff0000, v50
	v_mul_f32_e32 v120, v120, v128
	v_mul_f32_e32 v121, v121, v129
	v_cvt_pk_bf16_f32 v126, v120, v121
	v_lshlrev_b32_e32 v128, 16, v51
	v_and_b32_e32 v129, 0xffff0000, v51
	v_mul_f32_e32 v122, v122, v128
	v_mul_f32_e32 v123, v123, v129
	v_cvt_pk_bf16_f32 v127, v122, v123
	s_add_u32 s98, s12, 0x3000
	s_addc_u32 s99, s13, 0
	global_store_dwordx4 v2, v[124:127], s[98:99]
	v_lshlrev_b32_e32 v116, 16, v80
	v_and_b32_e32 v117, 0xffff0000, v80
	v_lshlrev_b32_e32 v118, 16, v81
	v_and_b32_e32 v119, 0xffff0000, v81
	v_lshlrev_b32_e32 v120, 16, v82
	v_and_b32_e32 v121, 0xffff0000, v82
	v_lshlrev_b32_e32 v122, 16, v83
	v_and_b32_e32 v123, 0xffff0000, v83
	v_pk_add_f32 v[100:101], v[100:101], v[116:117] neg_lo:[0,1] neg_hi:[0,1]
	v_pk_add_f32 v[102:103], v[102:103], v[118:119] neg_lo:[0,1] neg_hi:[0,1]
	v_pk_add_f32 v[104:105], v[104:105], v[120:121] neg_lo:[0,1] neg_hi:[0,1]
	v_pk_add_f32 v[106:107], v[106:107], v[122:123] neg_lo:[0,1] neg_hi:[0,1]
	s_add_u32 s98, s8, 0xb000
	s_addc_u32 s99, s9, 0
	global_load_dwordx4 v[16:19], v2, s[98:99]
	s_add_u32 s98, s10, 0xb000
	s_addc_u32 s99, s11, 0
	global_load_dwordx4 v[48:51], v2, s[98:99]
	s_add_u32 s98, s40, 0xb000
	s_addc_u32 s99, s41, 0
	global_load_dwordx4 v[80:83], v2, s[98:99]
	s_add_u32 s100, s100, 1
	s_waitcnt vmcnt(28)
	v_mov_b32_e32 v154, s38
	s_cmp_lt_u32 s100, s30
	s_cbranch_scc0 .Lpool_fa_4
	v_mov_b32_e32 v84, 0
	v_mov_b32_e32 v85, 0
	v_mov_b32_e32 v86, 0
	v_mov_b32_e32 v87, 0
	s_add_u32 s98, s100, 1
	v_cvt_f32_u32_e32 v116, s98
	v_div_scale_f32 v117, s[98:99], v116, v116, 1.0
	v_rcp_f32_e32 v118, v117
	s_nop 1
	v_fma_f32 v119, -v117, v118, 1.0
	v_fmac_f32_e32 v118, v119, v118
	v_div_scale_f32 v119, vcc, 1.0, v116, 1.0
	v_mul_f32_e32 v120, v119, v118
	v_fma_f32 v121, -v117, v120, v119
	v_fmac_f32_e32 v120, v121, v118
	v_fma_f32 v117, -v117, v120, v119
	s_nop 1
	v_div_fmas_f32 v117, v117, v118, v120
	v_div_fixup_f32 v154, v117, v116, 1.0
.Lpool_fa_4:
	v_lshlrev_b32_e32 v116, 16, v20
	v_and_b32_e32 v117, 0xffff0000, v20
	v_lshlrev_b32_e32 v118, 16, v21
	v_and_b32_e32 v119, 0xffff0000, v21
	v_lshlrev_b32_e32 v120, 16, v22
	v_and_b32_e32 v121, 0xffff0000, v22
	v_lshlrev_b32_e32 v122, 16, v23
	v_and_b32_e32 v123, 0xffff0000, v23
	v_pk_add_f32 v[100:101], v[100:101], v[116:117]
	v_pk_add_f32 v[102:103], v[102:103], v[118:119]
	v_pk_add_f32 v[104:105], v[104:105], v[120:121]
	v_pk_add_f32 v[106:107], v[106:107], v[122:123]
	v_fma_f32 v116, v154, v100, -v116
	v_fma_f32 v117, v154, v101, -v117
	v_fma_f32 v118, v154, v102, -v118
	v_fma_f32 v119, v154, v103, -v119
	v_fma_f32 v120, v154, v104, -v120
	v_fma_f32 v121, v154, v105, -v121
	v_fma_f32 v122, v154, v106, -v122
	v_fma_f32 v123, v154, v107, -v123
	v_mul_f32_e32 v116, v108, v116
	v_mul_f32_e32 v117, v109, v117
	v_mul_f32_e32 v118, v110, v118
	v_mul_f32_e32 v119, v111, v119
	v_mul_f32_e32 v120, v112, v120
	v_mul_f32_e32 v121, v113, v121
	v_mul_f32_e32 v122, v114, v122
	v_mul_f32_e32 v123, v115, v123
	v_lshlrev_b32_e32 v128, 16, v52
	v_and_b32_e32 v129, 0xffff0000, v52
	v_mul_f32_e32 v116, v116, v128
	v_mul_f32_e32 v117, v117, v129
	v_cvt_pk_bf16_f32 v124, v116, v117
	v_lshlrev_b32_e32 v128, 16, v53
	v_and_b32_e32 v129, 0xffff0000, v53
	v_mul_f32_e32 v118, v118, v128
	v_mul_f32_e32 v119, v119, v129
	v_cvt_pk_bf16_f32 v125, v118, v119
	v_lshlrev_b32_e32 v128, 16, v54
	v_and_b32_e32 v129, 0xffff0000, v54
	v_mul_f32_e32 v120, v120, v128
	v_mul_f32_e32 v121, v121, v129
	v_cvt_pk_bf16_f32 v126, v120, v121
	v_lshlrev_b32_e32 v128, 16, v55
	v_and_b32_e32 v129, 0xffff0000, v55
	v_mul_f32_e32 v122, v122, v128
	v_mul_f32_e32 v123, v123, v129
	v_cvt_pk_bf16_f32 v127, v122, v123
	s_add_u32 s98, s12, 0x4000
	s_addc_u32 s99, s13, 0
	global_store_dwordx4 v2, v[124:127], s[98:99]
	v_lshlrev_b32_e32 v116, 16, v84
	v_and_b32_e32 v117, 0xffff0000, v84
	v_lshlrev_b32_e32 v118, 16, v85
	v_and_b32_e32 v119, 0xffff0000, v85
	v_lshlrev_b32_e32 v120, 16, v86
	v_and_b32_e32 v121, 0xffff0000, v86
	v_lshlrev_b32_e32 v122, 16, v87
	v_and_b32_e32 v123, 0xffff0000, v87
	v_pk_add_f32 v[100:101], v[100:101], v[116:117] neg_lo:[0,1] neg_hi:[0,1]
	v_pk_add_f32 v[102:103], v[102:103], v[118:119] neg_lo:[0,1] neg_hi:[0,1]
	v_pk_add_f32 v[104:105], v[104:105], v[120:121] neg_lo:[0,1] neg_hi:[0,1]
	v_pk_add_f32 v[106:107], v[106:107], v[122:123] neg_lo:[0,1] neg_hi:[0,1]
	s_add_u32 s98, s8, 0xc000
	s_addc_u32 s99, s9, 0
	global_load_dwordx4 v[20:23], v2, s[98:99]
	s_add_u32 s98, s10, 0xc000
	s_addc_u32 s99, s11, 0
	global_load_dwordx4 v[52:55], v2, s[98:99]
	s_add_u32 s98, s40, 0xc000
	s_addc_u32 s99, s41, 0
	global_load_dwordx4 v[84:87], v2, s[98:99]
	s_add_u32 s100, s100, 1
	s_waitcnt vmcnt(28)
	v_mov_b32_e32 v154, s38
	s_cmp_lt_u32 s100, s30
	s_cbranch_scc0 .Lpool_fa_5
	v_mov_b32_e32 v88, 0
	v_mov_b32_e32 v89, 0
	v_mov_b32_e32 v90, 0
	v_mov_b32_e32 v91, 0
	s_add_u32 s98, s100, 1
	v_cvt_f32_u32_e32 v116, s98
	v_div_scale_f32 v117, s[98:99], v116, v116, 1.0
	v_rcp_f32_e32 v118, v117
	s_nop 1
	v_fma_f32 v119, -v117, v118, 1.0
	v_fmac_f32_e32 v118, v119, v118
	v_div_scale_f32 v119, vcc, 1.0, v116, 1.0
	v_mul_f32_e32 v120, v119, v118
	v_fma_f32 v121, -v117, v120, v119
	v_fmac_f32_e32 v120, v121, v118
	v_fma_f32 v117, -v117, v120, v119
	s_nop 1
	v_div_fmas_f32 v117, v117, v118, v120
	v_div_fixup_f32 v154, v117, v116, 1.0
.Lpool_fa_5:
	v_lshlrev_b32_e32 v116, 16, v24
	v_and_b32_e32 v117, 0xffff0000, v24
	v_lshlrev_b32_e32 v118, 16, v25
	v_and_b32_e32 v119, 0xffff0000, v25
	v_lshlrev_b32_e32 v120, 16, v26
	v_and_b32_e32 v121, 0xffff0000, v26
	v_lshlrev_b32_e32 v122, 16, v27
	v_and_b32_e32 v123, 0xffff0000, v27
	v_pk_add_f32 v[100:101], v[100:101], v[116:117]
	v_pk_add_f32 v[102:103], v[102:103], v[118:119]
	v_pk_add_f32 v[104:105], v[104:105], v[120:121]
	v_pk_add_f32 v[106:107], v[106:107], v[122:123]
	v_fma_f32 v116, v154, v100, -v116
	v_fma_f32 v117, v154, v101, -v117
	v_fma_f32 v118, v154, v102, -v118
	v_fma_f32 v119, v154, v103, -v119
	v_fma_f32 v120, v154, v104, -v120
	v_fma_f32 v121, v154, v105, -v121
	v_fma_f32 v122, v154, v106, -v122
	v_fma_f32 v123, v154, v107, -v123
	v_mul_f32_e32 v116, v108, v116
	v_mul_f32_e32 v117, v109, v117
	v_mul_f32_e32 v118, v110, v118
	v_mul_f32_e32 v119, v111, v119
	v_mul_f32_e32 v120, v112, v120
	v_mul_f32_e32 v121, v113, v121
	v_mul_f32_e32 v122, v114, v122
	v_mul_f32_e32 v123, v115, v123
	v_lshlrev_b32_e32 v128, 16, v56
	v_and_b32_e32 v129, 0xffff0000, v56
	v_mul_f32_e32 v116, v116, v128
	v_mul_f32_e32 v117, v117, v129
	v_cvt_pk_bf16_f32 v124, v116, v117
	v_lshlrev_b32_e32 v128, 16, v57
	v_and_b32_e32 v129, 0xffff0000, v57
	v_mul_f32_e32 v118, v118, v128
	v_mul_f32_e32 v119, v119, v129
	v_cvt_pk_bf16_f32 v125, v118, v119
	v_lshlrev_b32_e32 v128, 16, v58
	v_and_b32_e32 v129, 0xffff0000, v58
	v_mul_f32_e32 v120, v120, v128
	v_mul_f32_e32 v121, v121, v129
	v_cvt_pk_bf16_f32 v126, v120, v121
	v_lshlrev_b32_e32 v128, 16, v59
	v_and_b32_e32 v129, 0xffff0000, v59
	v_mul_f32_e32 v122, v122, v128
	v_mul_f32_e32 v123, v123, v129
	v_cvt_pk_bf16_f32 v127, v122, v123
	s_add_u32 s98, s12, 0x5000
	s_addc_u32 s99, s13, 0
	global_store_dwordx4 v2, v[124:127], s[98:99]
	v_lshlrev_b32_e32 v116, 16, v88
	v_and_b32_e32 v117, 0xffff0000, v88
	v_lshlrev_b32_e32 v118, 16, v89
	v_and_b32_e32 v119, 0xffff0000, v89
	v_lshlrev_b32_e32 v120, 16, v90
	v_and_b32_e32 v121, 0xffff0000, v90
	v_lshlrev_b32_e32 v122, 16, v91
	v_and_b32_e32 v123, 0xffff0000, v91
	v_pk_add_f32 v[100:101], v[100:101], v[116:117] neg_lo:[0,1] neg_hi:[0,1]
	v_pk_add_f32 v[102:103], v[102:103], v[118:119] neg_lo:[0,1] neg_hi:[0,1]
	v_pk_add_f32 v[104:105], v[104:105], v[120:121] neg_lo:[0,1] neg_hi:[0,1]
	v_pk_add_f32 v[106:107], v[106:107], v[122:123] neg_lo:[0,1] neg_hi:[0,1]
	s_add_u32 s98, s8, 0xd000
	s_addc_u32 s99, s9, 0
	global_load_dwordx4 v[24:27], v2, s[98:99]
	s_add_u32 s98, s10, 0xd000
	s_addc_u32 s99, s11, 0
	global_load_dwordx4 v[56:59], v2, s[98:99]
	s_add_u32 s98, s40, 0xd000
	s_addc_u32 s99, s41, 0
	global_load_dwordx4 v[88:91], v2, s[98:99]
	s_add_u32 s100, s100, 1
	s_waitcnt vmcnt(28)
	v_mov_b32_e32 v154, s38
	s_cmp_lt_u32 s100, s30
	s_cbranch_scc0 .Lpool_fa_6
	v_mov_b32_e32 v92, 0
	v_mov_b32_e32 v93, 0
	v_mov_b32_e32 v94, 0
	v_mov_b32_e32 v95, 0
	s_add_u32 s98, s100, 1
	v_cvt_f32_u32_e32 v116, s98
	v_div_scale_f32 v117, s[98:99], v116, v116, 1.0
	v_rcp_f32_e32 v118, v117
	s_nop 1
	v_fma_f32 v119, -v117, v118, 1.0
	v_fmac_f32_e32 v118, v119, v118
	v_div_scale_f32 v119, vcc, 1.0, v116, 1.0
	v_mul_f32_e32 v120, v119, v118
	v_fma_f32 v121, -v117, v120, v119
	v_fmac_f32_e32 v120, v121, v118
	v_fma_f32 v117, -v117, v120, v119
	s_nop 1
	v_div_fmas_f32 v117, v117, v118, v120
	v_div_fixup_f32 v154, v117, v116, 1.0
.Lpool_fa_6:
	v_lshlrev_b32_e32 v116, 16, v28
	v_and_b32_e32 v117, 0xffff0000, v28
	v_lshlrev_b32_e32 v118, 16, v29
	v_and_b32_e32 v119, 0xffff0000, v29
	v_lshlrev_b32_e32 v120, 16, v30
	v_and_b32_e32 v121, 0xffff0000, v30
	v_lshlrev_b32_e32 v122, 16, v31
	v_and_b32_e32 v123, 0xffff0000, v31
	v_pk_add_f32 v[100:101], v[100:101], v[116:117]
	v_pk_add_f32 v[102:103], v[102:103], v[118:119]
	v_pk_add_f32 v[104:105], v[104:105], v[120:121]
	v_pk_add_f32 v[106:107], v[106:107], v[122:123]
	v_fma_f32 v116, v154, v100, -v116
	v_fma_f32 v117, v154, v101, -v117
	v_fma_f32 v118, v154, v102, -v118
	v_fma_f32 v119, v154, v103, -v119
	v_fma_f32 v120, v154, v104, -v120
	v_fma_f32 v121, v154, v105, -v121
	v_fma_f32 v122, v154, v106, -v122
	v_fma_f32 v123, v154, v107, -v123
	v_mul_f32_e32 v116, v108, v116
	v_mul_f32_e32 v117, v109, v117
	v_mul_f32_e32 v118, v110, v118
	v_mul_f32_e32 v119, v111, v119
	v_mul_f32_e32 v120, v112, v120
	v_mul_f32_e32 v121, v113, v121
	v_mul_f32_e32 v122, v114, v122
	v_mul_f32_e32 v123, v115, v123
	v_lshlrev_b32_e32 v128, 16, v60
	v_and_b32_e32 v129, 0xffff0000, v60
	v_mul_f32_e32 v116, v116, v128
	v_mul_f32_e32 v117, v117, v129
	v_cvt_pk_bf16_f32 v124, v116, v117
	v_lshlrev_b32_e32 v128, 16, v61
	v_and_b32_e32 v129, 0xffff0000, v61
	v_mul_f32_e32 v118, v118, v128
	v_mul_f32_e32 v119, v119, v129
	v_cvt_pk_bf16_f32 v125, v118, v119
	v_lshlrev_b32_e32 v128, 16, v62
	v_and_b32_e32 v129, 0xffff0000, v62
	v_mul_f32_e32 v120, v120, v128
	v_mul_f32_e32 v121, v121, v129
	v_cvt_pk_bf16_f32 v126, v120, v121
	v_lshlrev_b32_e32 v128, 16, v63
	v_and_b32_e32 v129, 0xffff0000, v63
	v_mul_f32_e32 v122, v122, v128
	v_mul_f32_e32 v123, v123, v129
	v_cvt_pk_bf16_f32 v127, v122, v123
	s_add_u32 s98, s12, 0x6000
	s_addc_u32 s99, s13, 0
	global_store_dwordx4 v2, v[124:127], s[98:99]
	v_lshlrev_b32_e32 v116, 16, v92
	v_and_b32_e32 v117, 0xffff0000, v92
	v_lshlrev_b32_e32 v118, 16, v93
	v_and_b32_e32 v119, 0xffff0000, v93
	v_lshlrev_b32_e32 v120, 16, v94
	v_and_b32_e32 v121, 0xffff0000, v94
	v_lshlrev_b32_e32 v122, 16, v95
	v_and_b32_e32 v123, 0xffff0000, v95
	v_pk_add_f32 v[100:101], v[100:101], v[116:117] neg_lo:[0,1] neg_hi:[0,1]
	v_pk_add_f32 v[102:103], v[102:103], v[118:119] neg_lo:[0,1] neg_hi:[0,1]
	v_pk_add_f32 v[104:105], v[104:105], v[120:121] neg_lo:[0,1] neg_hi:[0,1]
	v_pk_add_f32 v[106:107], v[106:107], v[122:123] neg_lo:[0,1] neg_hi:[0,1]
	s_add_u32 s98, s8, 0xe000
	s_addc_u32 s99, s9, 0
	global_load_dwordx4 v[28:31], v2, s[98:99]
	s_add_u32 s98, s10, 0xe000
	s_addc_u32 s99, s11, 0
	global_load_dwordx4 v[60:63], v2, s[98:99]
	s_add_u32 s98, s40, 0xe000
	s_addc_u32 s99, s41, 0
	global_load_dwordx4 v[92:95], v2, s[98:99]
	s_add_u32 s100, s100, 1
	s_waitcnt vmcnt(28)
	v_mov_b32_e32 v154, s38
	s_cmp_lt_u32 s100, s30
	s_cbranch_scc0 .Lpool_fa_7
	v_mov_b32_e32 v96, 0
	v_mov_b32_e32 v97, 0
	v_mov_b32_e32 v98, 0
	v_mov_b32_e32 v99, 0
	s_add_u32 s98, s100, 1
	v_cvt_f32_u32_e32 v116, s98
	v_div_scale_f32 v117, s[98:99], v116, v116, 1.0
	v_rcp_f32_e32 v118, v117
	s_nop 1
	v_fma_f32 v119, -v117, v118, 1.0
	v_fmac_f32_e32 v118, v119, v118
	v_div_scale_f32 v119, vcc, 1.0, v116, 1.0
	v_mul_f32_e32 v120, v119, v118
	v_fma_f32 v121, -v117, v120, v119
	v_fmac_f32_e32 v120, v121, v118
	v_fma_f32 v117, -v117, v120, v119
	s_nop 1
	v_div_fmas_f32 v117, v117, v118, v120
	v_div_fixup_f32 v154, v117, v116, 1.0
.Lpool_fa_7:
	v_lshlrev_b32_e32 v116, 16, v32
	v_and_b32_e32 v117, 0xffff0000, v32
	v_lshlrev_b32_e32 v118, 16, v33
	v_and_b32_e32 v119, 0xffff0000, v33
	v_lshlrev_b32_e32 v120, 16, v34
	v_and_b32_e32 v121, 0xffff0000, v34
	v_lshlrev_b32_e32 v122, 16, v35
	v_and_b32_e32 v123, 0xffff0000, v35
	v_pk_add_f32 v[100:101], v[100:101], v[116:117]
	v_pk_add_f32 v[102:103], v[102:103], v[118:119]
	v_pk_add_f32 v[104:105], v[104:105], v[120:121]
	v_pk_add_f32 v[106:107], v[106:107], v[122:123]
	v_fma_f32 v116, v154, v100, -v116
	v_fma_f32 v117, v154, v101, -v117
	v_fma_f32 v118, v154, v102, -v118
	v_fma_f32 v119, v154, v103, -v119
	v_fma_f32 v120, v154, v104, -v120
	v_fma_f32 v121, v154, v105, -v121
	v_fma_f32 v122, v154, v106, -v122
	v_fma_f32 v123, v154, v107, -v123
	v_mul_f32_e32 v116, v108, v116
	v_mul_f32_e32 v117, v109, v117
	v_mul_f32_e32 v118, v110, v118
	v_mul_f32_e32 v119, v111, v119
	v_mul_f32_e32 v120, v112, v120
	v_mul_f32_e32 v121, v113, v121
	v_mul_f32_e32 v122, v114, v122
	v_mul_f32_e32 v123, v115, v123
	v_lshlrev_b32_e32 v128, 16, v64
	v_and_b32_e32 v129, 0xffff0000, v64
	v_mul_f32_e32 v116, v116, v128
	v_mul_f32_e32 v117, v117, v129
	v_cvt_pk_bf16_f32 v124, v116, v117
	v_lshlrev_b32_e32 v128, 16, v65
	v_and_b32_e32 v129, 0xffff0000, v65
	v_mul_f32_e32 v118, v118, v128
	v_mul_f32_e32 v119, v119, v129
	v_cvt_pk_bf16_f32 v125, v118, v119
	v_lshlrev_b32_e32 v128, 16, v66
	v_and_b32_e32 v129, 0xffff0000, v66
	v_mul_f32_e32 v120, v120, v128
	v_mul_f32_e32 v121, v121, v129
	v_cvt_pk_bf16_f32 v126, v120, v121
	v_lshlrev_b32_e32 v128, 16, v67
	v_and_b32_e32 v129, 0xffff0000, v67
	v_mul_f32_e32 v122, v122, v128
	v_mul_f32_e32 v123, v123, v129
	v_cvt_pk_bf16_f32 v127, v122, v123
	s_add_u32 s98, s12, 0x7000
	s_addc_u32 s99, s13, 0
	global_store_dwordx4 v2, v[124:127], s[98:99]
	v_lshlrev_b32_e32 v116, 16, v96
	v_and_b32_e32 v117, 0xffff0000, v96
	v_lshlrev_b32_e32 v118, 16, v97
	v_and_b32_e32 v119, 0xffff0000, v97
	v_lshlrev_b32_e32 v120, 16, v98
	v_and_b32_e32 v121, 0xffff0000, v98
	v_lshlrev_b32_e32 v122, 16, v99
	v_and_b32_e32 v123, 0xffff0000, v99
	v_pk_add_f32 v[100:101], v[100:101], v[116:117] neg_lo:[0,1] neg_hi:[0,1]
	v_pk_add_f32 v[102:103], v[102:103], v[118:119] neg_lo:[0,1] neg_hi:[0,1]
	v_pk_add_f32 v[104:105], v[104:105], v[120:121] neg_lo:[0,1] neg_hi:[0,1]
	v_pk_add_f32 v[106:107], v[106:107], v[122:123] neg_lo:[0,1] neg_hi:[0,1]
	s_add_u32 s98, s8, 0xf000
	s_addc_u32 s99, s9, 0
	global_load_dwordx4 v[32:35], v2, s[98:99]
	s_add_u32 s98, s10, 0xf000
	s_addc_u32 s99, s11, 0
	global_load_dwordx4 v[64:67], v2, s[98:99]
	s_add_u32 s98, s40, 0xf000
	s_addc_u32 s99, s41, 0
	global_load_dwordx4 v[96:99], v2, s[98:99]
	s_add_u32 s100, s100, 1
	s_add_u32 s8, s8, 0x8000
	s_addc_u32 s9, s9, 0
	s_add_u32 s10, s10, 0x8000
	s_addc_u32 s11, s11, 0
	s_add_u32 s12, s12, 0x8000
	s_addc_u32 s13, s13, 0
	s_add_u32 s40, s40, 0x8000
	s_addc_u32 s41, s41, 0
	s_sub_u32 s39, s39, 1
	s_cmp_lg_u32 s39, 0
	s_cbranch_scc1 .Lpool_batch
	s_waitcnt vmcnt(28)
	v_mov_b32_e32 v154, s38
	s_cmp_lt_u32 s100, s30
	s_cbranch_scc0 .Lpool_fb_0
	v_mov_b32_e32 v68, 0
	v_mov_b32_e32 v69, 0
	v_mov_b32_e32 v70, 0
	v_mov_b32_e32 v71, 0
	s_add_u32 s98, s100, 1
	v_cvt_f32_u32_e32 v116, s98
	v_div_scale_f32 v117, s[98:99], v116, v116, 1.0
	v_rcp_f32_e32 v118, v117
	s_nop 1
	v_fma_f32 v119, -v117, v118, 1.0
	v_fmac_f32_e32 v118, v119, v118
	v_div_scale_f32 v119, vcc, 1.0, v116, 1.0
	v_mul_f32_e32 v120, v119, v118
	v_fma_f32 v121, -v117, v120, v119
	v_fmac_f32_e32 v120, v121, v118
	v_fma_f32 v117, -v117, v120, v119
	s_nop 1
	v_div_fmas_f32 v117, v117, v118, v120
	v_div_fixup_f32 v154, v117, v116, 1.0
.Lpool_fb_0:
	v_lshlrev_b32_e32 v116, 16, v4
	v_and_b32_e32 v117, 0xffff0000, v4
	v_lshlrev_b32_e32 v118, 16, v5
	v_and_b32_e32 v119, 0xffff0000, v5
	v_lshlrev_b32_e32 v120, 16, v6
	v_and_b32_e32 v121, 0xffff0000, v6
	v_lshlrev_b32_e32 v122, 16, v7
	v_and_b32_e32 v123, 0xffff0000, v7
	v_pk_add_f32 v[100:101], v[100:101], v[116:117]
	v_pk_add_f32 v[102:103], v[102:103], v[118:119]
	v_pk_add_f32 v[104:105], v[104:105], v[120:121]
	v_pk_add_f32 v[106:107], v[106:107], v[122:123]
	v_fma_f32 v116, v154, v100, -v116
	v_fma_f32 v117, v154, v101, -v117
	v_fma_f32 v118, v154, v102, -v118
	v_fma_f32 v119, v154, v103, -v119
	v_fma_f32 v120, v154, v104, -v120
	v_fma_f32 v121, v154, v105, -v121
	v_fma_f32 v122, v154, v106, -v122
	v_fma_f32 v123, v154, v107, -v123
	v_mul_f32_e32 v116, v108, v116
	v_mul_f32_e32 v117, v109, v117
	v_mul_f32_e32 v118, v110, v118
	v_mul_f32_e32 v119, v111, v119
	v_mul_f32_e32 v120, v112, v120
	v_mul_f32_e32 v121, v113, v121
	v_mul_f32_e32 v122, v114, v122
	v_mul_f32_e32 v123, v115, v123
	v_lshlrev_b32_e32 v128, 16, v36
	v_and_b32_e32 v129, 0xffff0000, v36
	v_mul_f32_e32 v116, v116, v128
	v_mul_f32_e32 v117, v117, v129
	v_cvt_pk_bf16_f32 v124, v116, v117
	v_lshlrev_b32_e32 v128, 16, v37
	v_and_b32_e32 v129, 0xffff0000, v37
	v_mul_f32_e32 v118, v118, v128
	v_mul_f32_e32 v119, v119, v129
	v_cvt_pk_bf16_f32 v125, v118, v119
	v_lshlrev_b32_e32 v128, 16, v38
	v_and_b32_e32 v129, 0xffff0000, v38
	v_mul_f32_e32 v120, v120, v128
	v_mul_f32_e32 v121, v121, v129
	v_cvt_pk_bf16_f32 v126, v120, v121
	v_lshlrev_b32_e32 v128, 16, v39
	v_and_b32_e32 v129, 0xffff0000, v39
	v_mul_f32_e32 v122, v122, v128
	v_mul_f32_e32 v123, v123, v129
	v_cvt_pk_bf16_f32 v127, v122, v123
	s_add_u32 s98, s12, 0
	s_addc_u32 s99, s13, 0
	global_store_dwordx4 v2, v[124:127], s[98:99]
	v_lshlrev_b32_e32 v116, 16, v68
	v_and_b32_e32 v117, 0xffff0000, v68
	v_lshlrev_b32_e32 v118, 16, v69
	v_and_b32_e32 v119, 0xffff0000, v69
	v_lshlrev_b32_e32 v120, 16, v70
	v_and_b32_e32 v121, 0xffff0000, v70
	v_lshlrev_b32_e32 v122, 16, v71
	v_and_b32_e32 v123, 0xffff0000, v71
	v_pk_add_f32 v[100:101], v[100:101], v[116:117] neg_lo:[0,1] neg_hi:[0,1]
	v_pk_add_f32 v[102:103], v[102:103], v[118:119] neg_lo:[0,1] neg_hi:[0,1]
	v_pk_add_f32 v[104:105], v[104:105], v[120:121] neg_lo:[0,1] neg_hi:[0,1]
	v_pk_add_f32 v[106:107], v[106:107], v[122:123] neg_lo:[0,1] neg_hi:[0,1]
	s_add_u32 s100, s100, 1
	s_waitcnt vmcnt(25)
	v_mov_b32_e32 v154, s38
	s_cmp_lt_u32 s100, s30
	s_cbranch_scc0 .Lpool_fb_1
	v_mov_b32_e32 v72, 0
	v_mov_b32_e32 v73, 0
	v_mov_b32_e32 v74, 0
	v_mov_b32_e32 v75, 0
	s_add_u32 s98, s100, 1
	v_cvt_f32_u32_e32 v116, s98
	v_div_scale_f32 v117, s[98:99], v116, v116, 1.0
	v_rcp_f32_e32 v118, v117
	s_nop 1
	v_fma_f32 v119, -v117, v118, 1.0
	v_fmac_f32_e32 v118, v119, v118
	v_div_scale_f32 v119, vcc, 1.0, v116, 1.0
	v_mul_f32_e32 v120, v119, v118
	v_fma_f32 v121, -v117, v120, v119
	v_fmac_f32_e32 v120, v121, v118
	v_fma_f32 v117, -v117, v120, v119
	s_nop 1
	v_div_fmas_f32 v117, v117, v118, v120
	v_div_fixup_f32 v154, v117, v116, 1.0
.Lpool_fb_1:
	v_lshlrev_b32_e32 v116, 16, v8
	v_and_b32_e32 v117, 0xffff0000, v8
	v_lshlrev_b32_e32 v118, 16, v9
	v_and_b32_e32 v119, 0xffff0000, v9
	v_lshlrev_b32_e32 v120, 16, v10
	v_and_b32_e32 v121, 0xffff0000, v10
	v_lshlrev_b32_e32 v122, 16, v11
	v_and_b32_e32 v123, 0xffff0000, v11
	v_pk_add_f32 v[100:101], v[100:101], v[116:117]
	v_pk_add_f32 v[102:103], v[102:103], v[118:119]
	v_pk_add_f32 v[104:105], v[104:105], v[120:121]
	v_pk_add_f32 v[106:107], v[106:107], v[122:123]
	v_fma_f32 v116, v154, v100, -v116
	v_fma_f32 v117, v154, v101, -v117
	v_fma_f32 v118, v154, v102, -v118
	v_fma_f32 v119, v154, v103, -v119
	v_fma_f32 v120, v154, v104, -v120
	v_fma_f32 v121, v154, v105, -v121
	v_fma_f32 v122, v154, v106, -v122
	v_fma_f32 v123, v154, v107, -v123
	v_mul_f32_e32 v116, v108, v116
	v_mul_f32_e32 v117, v109, v117
	v_mul_f32_e32 v118, v110, v118
	v_mul_f32_e32 v119, v111, v119
	v_mul_f32_e32 v120, v112, v120
	v_mul_f32_e32 v121, v113, v121
	v_mul_f32_e32 v122, v114, v122
	v_mul_f32_e32 v123, v115, v123
	v_lshlrev_b32_e32 v128, 16, v40
	v_and_b32_e32 v129, 0xffff0000, v40
	v_mul_f32_e32 v116, v116, v128
	v_mul_f32_e32 v117, v117, v129
	v_cvt_pk_bf16_f32 v124, v116, v117
	v_lshlrev_b32_e32 v128, 16, v41
	v_and_b32_e32 v129, 0xffff0000, v41
	v_mul_f32_e32 v118, v118, v128
	v_mul_f32_e32 v119, v119, v129
	v_cvt_pk_bf16_f32 v125, v118, v119
	v_lshlrev_b32_e32 v128, 16, v42
	v_and_b32_e32 v129, 0xffff0000, v42
	v_mul_f32_e32 v120, v120, v128
	v_mul_f32_e32 v121, v121, v129
	v_cvt_pk_bf16_f32 v126, v120, v121
	v_lshlrev_b32_e32 v128, 16, v43
	v_and_b32_e32 v129, 0xffff0000, v43
	v_mul_f32_e32 v122, v122, v128
	v_mul_f32_e32 v123, v123, v129
	v_cvt_pk_bf16_f32 v127, v122, v123
	s_add_u32 s98, s12, 0x1000
	s_addc_u32 s99, s13, 0
	global_store_dwordx4 v2, v[124:127], s[98:99]
	v_lshlrev_b32_e32 v116, 16, v72
	v_and_b32_e32 v117, 0xffff0000, v72
	v_lshlrev_b32_e32 v118, 16, v73
	v_and_b32_e32 v119, 0xffff0000, v73
	v_lshlrev_b32_e32 v120, 16, v74
	v_and_b32_e32 v121, 0xffff0000, v74
	v_lshlrev_b32_e32 v122, 16, v75
	v_and_b32_e32 v123, 0xffff0000, v75
	v_pk_add_f32 v[100:101], v[100:101], v[116:117] neg_lo:[0,1] neg_hi:[0,1]
	v_pk_add_f32 v[102:103], v[102:103], v[118:119] neg_lo:[0,1] neg_hi:[0,1]
	v_pk_add_f32 v[104:105], v[104:105], v[120:121] neg_lo:[0,1] neg_hi:[0,1]
	v_pk_add_f32 v[106:107], v[106:107], v[122:123] neg_lo:[0,1] neg_hi:[0,1]
	s_add_u32 s100, s100, 1
	s_waitcnt vmcnt(22)
	v_mov_b32_e32 v154, s38
	s_cmp_lt_u32 s100, s30
	s_cbranch_scc0 .Lpool_fb_2
	v_mov_b32_e32 v76, 0
	v_mov_b32_e32 v77, 0
	v_mov_b32_e32 v78, 0
	v_mov_b32_e32 v79, 0
	s_add_u32 s98, s100, 1
	v_cvt_f32_u32_e32 v116, s98
	v_div_scale_f32 v117, s[98:99], v116, v116, 1.0
	v_rcp_f32_e32 v118, v117
	s_nop 1
	v_fma_f32 v119, -v117, v118, 1.0
	v_fmac_f32_e32 v118, v119, v118
	v_div_scale_f32 v119, vcc, 1.0, v116, 1.0
	v_mul_f32_e32 v120, v119, v118
	v_fma_f32 v121, -v117, v120, v119
	v_fmac_f32_e32 v120, v121, v118
	v_fma_f32 v117, -v117, v120, v119
	s_nop 1
	v_div_fmas_f32 v117, v117, v118, v120
	v_div_fixup_f32 v154, v117, v116, 1.0
.Lpool_fb_2:
	v_lshlrev_b32_e32 v116, 16, v12
	v_and_b32_e32 v117, 0xffff0000, v12
	v_lshlrev_b32_e32 v118, 16, v13
	v_and_b32_e32 v119, 0xffff0000, v13
	v_lshlrev_b32_e32 v120, 16, v14
	v_and_b32_e32 v121, 0xffff0000, v14
	v_lshlrev_b32_e32 v122, 16, v15
	v_and_b32_e32 v123, 0xffff0000, v15
	v_pk_add_f32 v[100:101], v[100:101], v[116:117]
	v_pk_add_f32 v[102:103], v[102:103], v[118:119]
	v_pk_add_f32 v[104:105], v[104:105], v[120:121]
	v_pk_add_f32 v[106:107], v[106:107], v[122:123]
	v_fma_f32 v116, v154, v100, -v116
	v_fma_f32 v117, v154, v101, -v117
	v_fma_f32 v118, v154, v102, -v118
	v_fma_f32 v119, v154, v103, -v119
	v_fma_f32 v120, v154, v104, -v120
	v_fma_f32 v121, v154, v105, -v121
	v_fma_f32 v122, v154, v106, -v122
	v_fma_f32 v123, v154, v107, -v123
	v_mul_f32_e32 v116, v108, v116
	v_mul_f32_e32 v117, v109, v117
	v_mul_f32_e32 v118, v110, v118
	v_mul_f32_e32 v119, v111, v119
	v_mul_f32_e32 v120, v112, v120
	v_mul_f32_e32 v121, v113, v121
	v_mul_f32_e32 v122, v114, v122
	v_mul_f32_e32 v123, v115, v123
	v_lshlrev_b32_e32 v128, 16, v44
	v_and_b32_e32 v129, 0xffff0000, v44
	v_mul_f32_e32 v116, v116, v128
	v_mul_f32_e32 v117, v117, v129
	v_cvt_pk_bf16_f32 v124, v116, v117
	v_lshlrev_b32_e32 v128, 16, v45
	v_and_b32_e32 v129, 0xffff0000, v45
	v_mul_f32_e32 v118, v118, v128
	v_mul_f32_e32 v119, v119, v129
	v_cvt_pk_bf16_f32 v125, v118, v119
	v_lshlrev_b32_e32 v128, 16, v46
	v_and_b32_e32 v129, 0xffff0000, v46
	v_mul_f32_e32 v120, v120, v128
	v_mul_f32_e32 v121, v121, v129
	v_cvt_pk_bf16_f32 v126, v120, v121
	v_lshlrev_b32_e32 v128, 16, v47
	v_and_b32_e32 v129, 0xffff0000, v47
	v_mul_f32_e32 v122, v122, v128
	v_mul_f32_e32 v123, v123, v129
	v_cvt_pk_bf16_f32 v127, v122, v123
	s_add_u32 s98, s12, 0x2000
	s_addc_u32 s99, s13, 0
	global_store_dwordx4 v2, v[124:127], s[98:99]
	v_lshlrev_b32_e32 v116, 16, v76
	v_and_b32_e32 v117, 0xffff0000, v76
	v_lshlrev_b32_e32 v118, 16, v77
	v_and_b32_e32 v119, 0xffff0000, v77
	v_lshlrev_b32_e32 v120, 16, v78
	v_and_b32_e32 v121, 0xffff0000, v78
	v_lshlrev_b32_e32 v122, 16, v79
	v_and_b32_e32 v123, 0xffff0000, v79
	v_pk_add_f32 v[100:101], v[100:101], v[116:117] neg_lo:[0,1] neg_hi:[0,1]
	v_pk_add_f32 v[102:103], v[102:103], v[118:119] neg_lo:[0,1] neg_hi:[0,1]
	v_pk_add_f32 v[104:105], v[104:105], v[120:121] neg_lo:[0,1] neg_hi:[0,1]
	v_pk_add_f32 v[106:107], v[106:107], v[122:123] neg_lo:[0,1] neg_hi:[0,1]
	s_add_u32 s100, s100, 1
	s_waitcnt vmcnt(19)
	v_mov_b32_e32 v154, s38
	s_cmp_lt_u32 s100, s30
	s_cbranch_scc0 .Lpool_fb_3
	v_mov_b32_e32 v80, 0
	v_mov_b32_e32 v81, 0
	v_mov_b32_e32 v82, 0
	v_mov_b32_e32 v83, 0
	s_add_u32 s98, s100, 1
	v_cvt_f32_u32_e32 v116, s98
	v_div_scale_f32 v117, s[98:99], v116, v116, 1.0
	v_rcp_f32_e32 v118, v117
	s_nop 1
	v_fma_f32 v119, -v117, v118, 1.0
	v_fmac_f32_e32 v118, v119, v118
	v_div_scale_f32 v119, vcc, 1.0, v116, 1.0
	v_mul_f32_e32 v120, v119, v118
	v_fma_f32 v121, -v117, v120, v119
	v_fmac_f32_e32 v120, v121, v118
	v_fma_f32 v117, -v117, v120, v119
	s_nop 1
	v_div_fmas_f32 v117, v117, v118, v120
	v_div_fixup_f32 v154, v117, v116, 1.0
.Lpool_fb_3:
	v_lshlrev_b32_e32 v116, 16, v16
	v_and_b32_e32 v117, 0xffff0000, v16
	v_lshlrev_b32_e32 v118, 16, v17
	v_and_b32_e32 v119, 0xffff0000, v17
	v_lshlrev_b32_e32 v120, 16, v18
	v_and_b32_e32 v121, 0xffff0000, v18
	v_lshlrev_b32_e32 v122, 16, v19
	v_and_b32_e32 v123, 0xffff0000, v19
	v_pk_add_f32 v[100:101], v[100:101], v[116:117]
	v_pk_add_f32 v[102:103], v[102:103], v[118:119]
	v_pk_add_f32 v[104:105], v[104:105], v[120:121]
	v_pk_add_f32 v[106:107], v[106:107], v[122:123]
	v_fma_f32 v116, v154, v100, -v116
	v_fma_f32 v117, v154, v101, -v117
	v_fma_f32 v118, v154, v102, -v118
	v_fma_f32 v119, v154, v103, -v119
	v_fma_f32 v120, v154, v104, -v120
	v_fma_f32 v121, v154, v105, -v121
	v_fma_f32 v122, v154, v106, -v122
	v_fma_f32 v123, v154, v107, -v123
	v_mul_f32_e32 v116, v108, v116
	v_mul_f32_e32 v117, v109, v117
	v_mul_f32_e32 v118, v110, v118
	v_mul_f32_e32 v119, v111, v119
	v_mul_f32_e32 v120, v112, v120
	v_mul_f32_e32 v121, v113, v121
	v_mul_f32_e32 v122, v114, v122
	v_mul_f32_e32 v123, v115, v123
	v_lshlrev_b32_e32 v128, 16, v48
	v_and_b32_e32 v129, 0xffff0000, v48
	v_mul_f32_e32 v116, v116, v128
	v_mul_f32_e32 v117, v117, v129
	v_cvt_pk_bf16_f32 v124, v116, v117
	v_lshlrev_b32_e32 v128, 16, v49
	v_and_b32_e32 v129, 0xffff0000, v49
	v_mul_f32_e32 v118, v118, v128
	v_mul_f32_e32 v119, v119, v129
	v_cvt_pk_bf16_f32 v125, v118, v119
	v_lshlrev_b32_e32 v128, 16, v50
	v_and_b32_e32 v129, 0xffff0000, v50
	v_mul_f32_e32 v120, v120, v128
	v_mul_f32_e32 v121, v121, v129
	v_cvt_pk_bf16_f32 v126, v120, v121
	v_lshlrev_b32_e32 v128, 16, v51
	v_and_b32_e32 v129, 0xffff0000, v51
	v_mul_f32_e32 v122, v122, v128
	v_mul_f32_e32 v123, v123, v129
	v_cvt_pk_bf16_f32 v127, v122, v123
	s_add_u32 s98, s12, 0x3000
	s_addc_u32 s99, s13, 0
	global_store_dwordx4 v2, v[124:127], s[98:99]
	v_lshlrev_b32_e32 v116, 16, v80
	v_and_b32_e32 v117, 0xffff0000, v80
	v_lshlrev_b32_e32 v118, 16, v81
	v_and_b32_e32 v119, 0xffff0000, v81
	v_lshlrev_b32_e32 v120, 16, v82
	v_and_b32_e32 v121, 0xffff0000, v82
	v_lshlrev_b32_e32 v122, 16, v83
	v_and_b32_e32 v123, 0xffff0000, v83
	v_pk_add_f32 v[100:101], v[100:101], v[116:117] neg_lo:[0,1] neg_hi:[0,1]
	v_pk_add_f32 v[102:103], v[102:103], v[118:119] neg_lo:[0,1] neg_hi:[0,1]
	v_pk_add_f32 v[104:105], v[104:105], v[120:121] neg_lo:[0,1] neg_hi:[0,1]
	v_pk_add_f32 v[106:107], v[106:107], v[122:123] neg_lo:[0,1] neg_hi:[0,1]
	s_add_u32 s100, s100, 1
	s_waitcnt vmcnt(16)
	v_mov_b32_e32 v154, s38
	s_cmp_lt_u32 s100, s30
	s_cbranch_scc0 .Lpool_fb_4
	v_mov_b32_e32 v84, 0
	v_mov_b32_e32 v85, 0
	v_mov_b32_e32 v86, 0
	v_mov_b32_e32 v87, 0
	s_add_u32 s98, s100, 1
	v_cvt_f32_u32_e32 v116, s98
	v_div_scale_f32 v117, s[98:99], v116, v116, 1.0
	v_rcp_f32_e32 v118, v117
	s_nop 1
	v_fma_f32 v119, -v117, v118, 1.0
	v_fmac_f32_e32 v118, v119, v118
	v_div_scale_f32 v119, vcc, 1.0, v116, 1.0
	v_mul_f32_e32 v120, v119, v118
	v_fma_f32 v121, -v117, v120, v119
	v_fmac_f32_e32 v120, v121, v118
	v_fma_f32 v117, -v117, v120, v119
	s_nop 1
	v_div_fmas_f32 v117, v117, v118, v120
	v_div_fixup_f32 v154, v117, v116, 1.0
.Lpool_fb_4:
	v_lshlrev_b32_e32 v116, 16, v20
	v_and_b32_e32 v117, 0xffff0000, v20
	v_lshlrev_b32_e32 v118, 16, v21
	v_and_b32_e32 v119, 0xffff0000, v21
	v_lshlrev_b32_e32 v120, 16, v22
	v_and_b32_e32 v121, 0xffff0000, v22
	v_lshlrev_b32_e32 v122, 16, v23
	v_and_b32_e32 v123, 0xffff0000, v23
	v_pk_add_f32 v[100:101], v[100:101], v[116:117]
	v_pk_add_f32 v[102:103], v[102:103], v[118:119]
	v_pk_add_f32 v[104:105], v[104:105], v[120:121]
	v_pk_add_f32 v[106:107], v[106:107], v[122:123]
	v_fma_f32 v116, v154, v100, -v116
	v_fma_f32 v117, v154, v101, -v117
	v_fma_f32 v118, v154, v102, -v118
	v_fma_f32 v119, v154, v103, -v119
	v_fma_f32 v120, v154, v104, -v120
	v_fma_f32 v121, v154, v105, -v121
	v_fma_f32 v122, v154, v106, -v122
	v_fma_f32 v123, v154, v107, -v123
	v_mul_f32_e32 v116, v108, v116
	v_mul_f32_e32 v117, v109, v117
	v_mul_f32_e32 v118, v110, v118
	v_mul_f32_e32 v119, v111, v119
	v_mul_f32_e32 v120, v112, v120
	v_mul_f32_e32 v121, v113, v121
	v_mul_f32_e32 v122, v114, v122
	v_mul_f32_e32 v123, v115, v123
	v_lshlrev_b32_e32 v128, 16, v52
	v_and_b32_e32 v129, 0xffff0000, v52
	v_mul_f32_e32 v116, v116, v128
	v_mul_f32_e32 v117, v117, v129
	v_cvt_pk_bf16_f32 v124, v116, v117
	v_lshlrev_b32_e32 v128, 16, v53
	v_and_b32_e32 v129, 0xffff0000, v53
	v_mul_f32_e32 v118, v118, v128
	v_mul_f32_e32 v119, v119, v129
	v_cvt_pk_bf16_f32 v125, v118, v119
	v_lshlrev_b32_e32 v128, 16, v54
	v_and_b32_e32 v129, 0xffff0000, v54
	v_mul_f32_e32 v120, v120, v128
	v_mul_f32_e32 v121, v121, v129
	v_cvt_pk_bf16_f32 v126, v120, v121
	v_lshlrev_b32_e32 v128, 16, v55
	v_and_b32_e32 v129, 0xffff0000, v55
	v_mul_f32_e32 v122, v122, v128
	v_mul_f32_e32 v123, v123, v129
	v_cvt_pk_bf16_f32 v127, v122, v123
	s_add_u32 s98, s12, 0x4000
	s_addc_u32 s99, s13, 0
	global_store_dwordx4 v2, v[124:127], s[98:99]
	v_lshlrev_b32_e32 v116, 16, v84
	v_and_b32_e32 v117, 0xffff0000, v84
	v_lshlrev_b32_e32 v118, 16, v85
	v_and_b32_e32 v119, 0xffff0000, v85
	v_lshlrev_b32_e32 v120, 16, v86
	v_and_b32_e32 v121, 0xffff0000, v86
	v_lshlrev_b32_e32 v122, 16, v87
	v_and_b32_e32 v123, 0xffff0000, v87
	v_pk_add_f32 v[100:101], v[100:101], v[116:117] neg_lo:[0,1] neg_hi:[0,1]
	v_pk_add_f32 v[102:103], v[102:103], v[118:119] neg_lo:[0,1] neg_hi:[0,1]
	v_pk_add_f32 v[104:105], v[104:105], v[120:121] neg_lo:[0,1] neg_hi:[0,1]
	v_pk_add_f32 v[106:107], v[106:107], v[122:123] neg_lo:[0,1] neg_hi:[0,1]
	s_add_u32 s100, s100, 1
	s_waitcnt vmcnt(13)
	v_mov_b32_e32 v154, s38
	s_cmp_lt_u32 s100, s30
	s_cbranch_scc0 .Lpool_fb_5
	v_mov_b32_e32 v88, 0
	v_mov_b32_e32 v89, 0
	v_mov_b32_e32 v90, 0
	v_mov_b32_e32 v91, 0
	s_add_u32 s98, s100, 1
	v_cvt_f32_u32_e32 v116, s98
	v_div_scale_f32 v117, s[98:99], v116, v116, 1.0
	v_rcp_f32_e32 v118, v117
	s_nop 1
	v_fma_f32 v119, -v117, v118, 1.0
	v_fmac_f32_e32 v118, v119, v118
	v_div_scale_f32 v119, vcc, 1.0, v116, 1.0
	v_mul_f32_e32 v120, v119, v118
	v_fma_f32 v121, -v117, v120, v119
	v_fmac_f32_e32 v120, v121, v118
	v_fma_f32 v117, -v117, v120, v119
	s_nop 1
	v_div_fmas_f32 v117, v117, v118, v120
	v_div_fixup_f32 v154, v117, v116, 1.0
.Lpool_fb_5:
	v_lshlrev_b32_e32 v116, 16, v24
	v_and_b32_e32 v117, 0xffff0000, v24
	v_lshlrev_b32_e32 v118, 16, v25
	v_and_b32_e32 v119, 0xffff0000, v25
	v_lshlrev_b32_e32 v120, 16, v26
	v_and_b32_e32 v121, 0xffff0000, v26
	v_lshlrev_b32_e32 v122, 16, v27
	v_and_b32_e32 v123, 0xffff0000, v27
	v_pk_add_f32 v[100:101], v[100:101], v[116:117]
	v_pk_add_f32 v[102:103], v[102:103], v[118:119]
	v_pk_add_f32 v[104:105], v[104:105], v[120:121]
	v_pk_add_f32 v[106:107], v[106:107], v[122:123]
	v_fma_f32 v116, v154, v100, -v116
	v_fma_f32 v117, v154, v101, -v117
	v_fma_f32 v118, v154, v102, -v118
	v_fma_f32 v119, v154, v103, -v119
	v_fma_f32 v120, v154, v104, -v120
	v_fma_f32 v121, v154, v105, -v121
	v_fma_f32 v122, v154, v106, -v122
	v_fma_f32 v123, v154, v107, -v123
	v_mul_f32_e32 v116, v108, v116
	v_mul_f32_e32 v117, v109, v117
	v_mul_f32_e32 v118, v110, v118
	v_mul_f32_e32 v119, v111, v119
	v_mul_f32_e32 v120, v112, v120
	v_mul_f32_e32 v121, v113, v121
	v_mul_f32_e32 v122, v114, v122
	v_mul_f32_e32 v123, v115, v123
	v_lshlrev_b32_e32 v128, 16, v56
	v_and_b32_e32 v129, 0xffff0000, v56
	v_mul_f32_e32 v116, v116, v128
	v_mul_f32_e32 v117, v117, v129
	v_cvt_pk_bf16_f32 v124, v116, v117
	v_lshlrev_b32_e32 v128, 16, v57
	v_and_b32_e32 v129, 0xffff0000, v57
	v_mul_f32_e32 v118, v118, v128
	v_mul_f32_e32 v119, v119, v129
	v_cvt_pk_bf16_f32 v125, v118, v119
	v_lshlrev_b32_e32 v128, 16, v58
	v_and_b32_e32 v129, 0xffff0000, v58
	v_mul_f32_e32 v120, v120, v128
	v_mul_f32_e32 v121, v121, v129
	v_cvt_pk_bf16_f32 v126, v120, v121
	v_lshlrev_b32_e32 v128, 16, v59
	v_and_b32_e32 v129, 0xffff0000, v59
	v_mul_f32_e32 v122, v122, v128
	v_mul_f32_e32 v123, v123, v129
	v_cvt_pk_bf16_f32 v127, v122, v123
	s_add_u32 s98, s12, 0x5000
	s_addc_u32 s99, s13, 0
	global_store_dwordx4 v2, v[124:127], s[98:99]
	v_lshlrev_b32_e32 v116, 16, v88
	v_and_b32_e32 v117, 0xffff0000, v88
	v_lshlrev_b32_e32 v118, 16, v89
	v_and_b32_e32 v119, 0xffff0000, v89
	v_lshlrev_b32_e32 v120, 16, v90
	v_and_b32_e32 v121, 0xffff0000, v90
	v_lshlrev_b32_e32 v122, 16, v91
	v_and_b32_e32 v123, 0xffff0000, v91
	v_pk_add_f32 v[100:101], v[100:101], v[116:117] neg_lo:[0,1] neg_hi:[0,1]
	v_pk_add_f32 v[102:103], v[102:103], v[118:119] neg_lo:[0,1] neg_hi:[0,1]
	v_pk_add_f32 v[104:105], v[104:105], v[120:121] neg_lo:[0,1] neg_hi:[0,1]
	v_pk_add_f32 v[106:107], v[106:107], v[122:123] neg_lo:[0,1] neg_hi:[0,1]
	s_add_u32 s100, s100, 1
	s_waitcnt vmcnt(10)
	v_mov_b32_e32 v154, s38
	s_cmp_lt_u32 s100, s30
	s_cbranch_scc0 .Lpool_fb_6
	v_mov_b32_e32 v92, 0
	v_mov_b32_e32 v93, 0
	v_mov_b32_e32 v94, 0
	v_mov_b32_e32 v95, 0
	s_add_u32 s98, s100, 1
	v_cvt_f32_u32_e32 v116, s98
	v_div_scale_f32 v117, s[98:99], v116, v116, 1.0
	v_rcp_f32_e32 v118, v117
	s_nop 1
	v_fma_f32 v119, -v117, v118, 1.0
	v_fmac_f32_e32 v118, v119, v118
	v_div_scale_f32 v119, vcc, 1.0, v116, 1.0
	v_mul_f32_e32 v120, v119, v118
	v_fma_f32 v121, -v117, v120, v119
	v_fmac_f32_e32 v120, v121, v118
	v_fma_f32 v117, -v117, v120, v119
	s_nop 1
	v_div_fmas_f32 v117, v117, v118, v120
	v_div_fixup_f32 v154, v117, v116, 1.0
.Lpool_fb_6:
	v_lshlrev_b32_e32 v116, 16, v28
	v_and_b32_e32 v117, 0xffff0000, v28
	v_lshlrev_b32_e32 v118, 16, v29
	v_and_b32_e32 v119, 0xffff0000, v29
	v_lshlrev_b32_e32 v120, 16, v30
	v_and_b32_e32 v121, 0xffff0000, v30
	v_lshlrev_b32_e32 v122, 16, v31
	v_and_b32_e32 v123, 0xffff0000, v31
	v_pk_add_f32 v[100:101], v[100:101], v[116:117]
	v_pk_add_f32 v[102:103], v[102:103], v[118:119]
	v_pk_add_f32 v[104:105], v[104:105], v[120:121]
	v_pk_add_f32 v[106:107], v[106:107], v[122:123]
	v_fma_f32 v116, v154, v100, -v116
	v_fma_f32 v117, v154, v101, -v117
	v_fma_f32 v118, v154, v102, -v118
	v_fma_f32 v119, v154, v103, -v119
	v_fma_f32 v120, v154, v104, -v120
	v_fma_f32 v121, v154, v105, -v121
	v_fma_f32 v122, v154, v106, -v122
	v_fma_f32 v123, v154, v107, -v123
	v_mul_f32_e32 v116, v108, v116
	v_mul_f32_e32 v117, v109, v117
	v_mul_f32_e32 v118, v110, v118
	v_mul_f32_e32 v119, v111, v119
	v_mul_f32_e32 v120, v112, v120
	v_mul_f32_e32 v121, v113, v121
	v_mul_f32_e32 v122, v114, v122
	v_mul_f32_e32 v123, v115, v123
	v_lshlrev_b32_e32 v128, 16, v60
	v_and_b32_e32 v129, 0xffff0000, v60
	v_mul_f32_e32 v116, v116, v128
	v_mul_f32_e32 v117, v117, v129
	v_cvt_pk_bf16_f32 v124, v116, v117
	v_lshlrev_b32_e32 v128, 16, v61
	v_and_b32_e32 v129, 0xffff0000, v61
	v_mul_f32_e32 v118, v118, v128
	v_mul_f32_e32 v119, v119, v129
	v_cvt_pk_bf16_f32 v125, v118, v119
	v_lshlrev_b32_e32 v128, 16, v62
	v_and_b32_e32 v129, 0xffff0000, v62
	v_mul_f32_e32 v120, v120, v128
	v_mul_f32_e32 v121, v121, v129
	v_cvt_pk_bf16_f32 v126, v120, v121
	v_lshlrev_b32_e32 v128, 16, v63
	v_and_b32_e32 v129, 0xffff0000, v63
	v_mul_f32_e32 v122, v122, v128
	v_mul_f32_e32 v123, v123, v129
	v_cvt_pk_bf16_f32 v127, v122, v123
	s_add_u32 s98, s12, 0x6000
	s_addc_u32 s99, s13, 0
	global_store_dwordx4 v2, v[124:127], s[98:99]
	v_lshlrev_b32_e32 v116, 16, v92
	v_and_b32_e32 v117, 0xffff0000, v92
	v_lshlrev_b32_e32 v118, 16, v93
	v_and_b32_e32 v119, 0xffff0000, v93
	v_lshlrev_b32_e32 v120, 16, v94
	v_and_b32_e32 v121, 0xffff0000, v94
	v_lshlrev_b32_e32 v122, 16, v95
	v_and_b32_e32 v123, 0xffff0000, v95
	v_pk_add_f32 v[100:101], v[100:101], v[116:117] neg_lo:[0,1] neg_hi:[0,1]
	v_pk_add_f32 v[102:103], v[102:103], v[118:119] neg_lo:[0,1] neg_hi:[0,1]
	v_pk_add_f32 v[104:105], v[104:105], v[120:121] neg_lo:[0,1] neg_hi:[0,1]
	v_pk_add_f32 v[106:107], v[106:107], v[122:123] neg_lo:[0,1] neg_hi:[0,1]
	s_add_u32 s100, s100, 1
	s_waitcnt vmcnt(7)
	v_mov_b32_e32 v154, s38
	s_cmp_lt_u32 s100, s30
	s_cbranch_scc0 .Lpool_fb_7
	v_mov_b32_e32 v96, 0
	v_mov_b32_e32 v97, 0
	v_mov_b32_e32 v98, 0
	v_mov_b32_e32 v99, 0
	s_add_u32 s98, s100, 1
	v_cvt_f32_u32_e32 v116, s98
	v_div_scale_f32 v117, s[98:99], v116, v116, 1.0
	v_rcp_f32_e32 v118, v117
	s_nop 1
	v_fma_f32 v119, -v117, v118, 1.0
	v_fmac_f32_e32 v118, v119, v118
	v_div_scale_f32 v119, vcc, 1.0, v116, 1.0
	v_mul_f32_e32 v120, v119, v118
	v_fma_f32 v121, -v117, v120, v119
	v_fmac_f32_e32 v120, v121, v118
	v_fma_f32 v117, -v117, v120, v119
	s_nop 1
	v_div_fmas_f32 v117, v117, v118, v120
	v_div_fixup_f32 v154, v117, v116, 1.0
.Lpool_fb_7:
	v_lshlrev_b32_e32 v116, 16, v32
	v_and_b32_e32 v117, 0xffff0000, v32
	v_lshlrev_b32_e32 v118, 16, v33
	v_and_b32_e32 v119, 0xffff0000, v33
	v_lshlrev_b32_e32 v120, 16, v34
	v_and_b32_e32 v121, 0xffff0000, v34
	v_lshlrev_b32_e32 v122, 16, v35
	v_and_b32_e32 v123, 0xffff0000, v35
	v_pk_add_f32 v[100:101], v[100:101], v[116:117]
	v_pk_add_f32 v[102:103], v[102:103], v[118:119]
	v_pk_add_f32 v[104:105], v[104:105], v[120:121]
	v_pk_add_f32 v[106:107], v[106:107], v[122:123]
	v_fma_f32 v116, v154, v100, -v116
	v_fma_f32 v117, v154, v101, -v117
	v_fma_f32 v118, v154, v102, -v118
	v_fma_f32 v119, v154, v103, -v119
	v_fma_f32 v120, v154, v104, -v120
	v_fma_f32 v121, v154, v105, -v121
	v_fma_f32 v122, v154, v106, -v122
	v_fma_f32 v123, v154, v107, -v123
	v_mul_f32_e32 v116, v108, v116
	v_mul_f32_e32 v117, v109, v117
	v_mul_f32_e32 v118, v110, v118
	v_mul_f32_e32 v119, v111, v119
	v_mul_f32_e32 v120, v112, v120
	v_mul_f32_e32 v121, v113, v121
	v_mul_f32_e32 v122, v114, v122
	v_mul_f32_e32 v123, v115, v123
	v_lshlrev_b32_e32 v128, 16, v64
	v_and_b32_e32 v129, 0xffff0000, v64
	v_mul_f32_e32 v116, v116, v128
	v_mul_f32_e32 v117, v117, v129
	v_cvt_pk_bf16_f32 v124, v116, v117
	v_lshlrev_b32_e32 v128, 16, v65
	v_and_b32_e32 v129, 0xffff0000, v65
	v_mul_f32_e32 v118, v118, v128
	v_mul_f32_e32 v119, v119, v129
	v_cvt_pk_bf16_f32 v125, v118, v119
	v_lshlrev_b32_e32 v128, 16, v66
	v_and_b32_e32 v129, 0xffff0000, v66
	v_mul_f32_e32 v120, v120, v128
	v_mul_f32_e32 v121, v121, v129
	v_cvt_pk_bf16_f32 v126, v120, v121
	v_lshlrev_b32_e32 v128, 16, v67
	v_and_b32_e32 v129, 0xffff0000, v67
	v_mul_f32_e32 v122, v122, v128
	v_mul_f32_e32 v123, v123, v129
	v_cvt_pk_bf16_f32 v127, v122, v123
	s_add_u32 s98, s12, 0x7000
	s_addc_u32 s99, s13, 0
	global_store_dwordx4 v2, v[124:127], s[98:99]
	v_lshlrev_b32_e32 v116, 16, v96
	v_and_b32_e32 v117, 0xffff0000, v96
	v_lshlrev_b32_e32 v118, 16, v97
	v_and_b32_e32 v119, 0xffff0000, v97
	v_lshlrev_b32_e32 v120, 16, v98
	v_and_b32_e32 v121, 0xffff0000, v98
	v_lshlrev_b32_e32 v122, 16, v99
	v_and_b32_e32 v123, 0xffff0000, v99
	v_pk_add_f32 v[100:101], v[100:101], v[116:117] neg_lo:[0,1] neg_hi:[0,1]
	v_pk_add_f32 v[102:103], v[102:103], v[118:119] neg_lo:[0,1] neg_hi:[0,1]
	v_pk_add_f32 v[104:105], v[104:105], v[120:121] neg_lo:[0,1] neg_hi:[0,1]
	v_pk_add_f32 v[106:107], v[106:107], v[122:123] neg_lo:[0,1] neg_hi:[0,1]
	s_add_u32 s100, s100, 1
	s_mov_b64 s[38:39], exec

	.amdhsa_kernel _Z4mega6Params
		.amdhsa_group_segment_fixed_size 0
		.amdhsa_private_segment_fixed_size 0
		.amdhsa_kernarg_size 384
		.amdhsa_user_sgpr_count 2
		.amdhsa_user_sgpr_dispatch_ptr 0
		.amdhsa_user_sgpr_queue_ptr 0
		.amdhsa_user_sgpr_kernarg_segment_ptr 1
		.amdhsa_user_sgpr_dispatch_id 0
		.amdhsa_user_sgpr_kernarg_preload_length 0
		.amdhsa_user_sgpr_kernarg_preload_offset 0
		.amdhsa_user_sgpr_private_segment_size 0
		.amdhsa_uses_dynamic_stack 0
		.amdhsa_enable_private_segment 0
		.amdhsa_system_sgpr_workgroup_id_x 1
		.amdhsa_system_sgpr_workgroup_id_y 0
		.amdhsa_system_sgpr_workgroup_id_z 0
		.amdhsa_system_sgpr_workgroup_info 0
		.amdhsa_system_vgpr_workitem_id 2
		.amdhsa_next_free_vgpr 243
		.amdhsa_next_free_sgpr 102
		.amdhsa_accum_offset 244
		.amdhsa_reserve_vcc 1
		.amdhsa_float_round_mode_32 0
		.amdhsa_float_round_mode_16_64 0
		.amdhsa_float_denorm_mode_32 3
		.amdhsa_float_denorm_mode_16_64 3
		.amdhsa_dx10_clamp 1
		.amdhsa_ieee_mode 1
		.amdhsa_fp16_overflow 0
		.amdhsa_tg_split 0
		.amdhsa_exception_fp_ieee_invalid_op 0
		.amdhsa_exception_fp_denorm_src 0
		.amdhsa_exception_fp_ieee_div_zero 0
		.amdhsa_exception_fp_ieee_overflow 0
		.amdhsa_exception_fp_ieee_underflow 0
		.amdhsa_exception_fp_ieee_inexact 0
		.amdhsa_exception_int_div_zero 0
	.end_amdhsa_kernel

amdhsa.kernels:
  - .agpr_count:     0
    .args:
      - .offset:         0
        .size:           128
        .value_kind:     by_value
      - .offset:         128
        .size:           4
        .value_kind:     hidden_block_count_x
      - .offset:         132
        .size:           4
        .value_kind:     hidden_block_count_y
      - .offset:         136
        .size:           4
        .value_kind:     hidden_block_count_z
      - .offset:         140
        .size:           2
        .value_kind:     hidden_group_size_x
      - .offset:         142
        .size:           2
        .value_kind:     hidden_group_size_y
      - .offset:         144
        .size:           2
        .value_kind:     hidden_group_size_z
      - .offset:         146
        .size:           2
        .value_kind:     hidden_remainder_x
      - .offset:         148
        .size:           2
        .value_kind:     hidden_remainder_y
      - .offset:         150
        .size:           2
        .value_kind:     hidden_remainder_z
      - .offset:         168
        .size:           8
        .value_kind:     hidden_global_offset_x
      - .offset:         176
        .size:           8
        .value_kind:     hidden_global_offset_y
      - .offset:         184
        .size:           8
        .value_kind:     hidden_global_offset_z
      - .offset:         192
        .size:           2
        .value_kind:     hidden_grid_dims
      - .offset:         216
        .size:           8
        .value_kind:     hidden_multigrid_sync_arg
      - .offset:         248
        .size:           4
        .value_kind:     hidden_dynamic_lds_size
    .group_segment_fixed_size: 0
    .kernarg_segment_align: 8
    .kernarg_segment_size: 384
    .language:       OpenCL C
    .language_version:
      - 2
      - 0
    .max_flat_workgroup_size: 512
    .name:           _Z4mega6Params
    .private_segment_fixed_size: 0
    .sgpr_count:     108
    .sgpr_spill_count: 146
    .symbol:         _Z4mega6Params.kd
    .uniform_work_group_size: 1
    .uses_dynamic_stack: false
    .vgpr_count:     243
    .vgpr_spill_count: 0
    .wavefront_size: 64
